# C1 LoRA (lw/la) products moved from 2048 v_dot2c per thread to v_mfma_f32_16x16x32_bf16 (same bf16 operands, f32 accumulate) with LDS staging back to the epilogue's registers
# speedup vs baseline: 1.0265x; 1.0098x over previous
; __device__ __forceinline__ unsigned cvtpk(float lo, float hi) { unsigned r; asm volatile("v_cvt_pk_bf16_f32 %0, %1, %2" : "=v"(r) : "v"(lo), "v"(hi)); return r; }
; __device__ __forceinline__ float sigmoidf_(float x) { return __builtin_amdgcn_rcpf(1.0f + __expf(-x)); }
; __global__ void __launch_bounds__(NWAVES * 64, 2) mk_fwd(Args args) {
;     ...
;                 for (int tile = bx; tile < M / 16; tile += G) {
;     ...
;                         dec[0] = __expf(-0.6065306597126334f * sigmoidf_(w0v.x + lw[tok][0])); dec[1] = __expf(-0.6065306597126334f * sigmoidf_(w0v.y + lw[tok][1]));
;                         aa[0] = sigmoidf_(a0v.x + la[tok][0]); aa[1] = sigmoidf_(a0v.y + la[tok][1]);
;                         kkn[0] = kk[0] * kkw.x; kkn[1] = kk[1] * kkw.y;
;                         const float ssq = sum32(kkn[0] * kkn[0] + kkn[1] * kkn[1]);
;                         const float inv = rsqrtf(ssq + 1e-12f);
;                         kkn[0] *= inv; kkn[1] *= inv;
;                         km[0] = kk[0] * (1.f + (aa[0] - 1.f) * kaw.x); km[1] = kk[1] * (1.f + (aa[1] - 1.f) * kaw.y);
;                         bb[0] = kkn[0] * aa[0]; bb[1] = kkn[1] * aa[1];
;                         const float rkd = sum32(rr[0] * km[0] * rkw.x + rr[1] * km[1] * rkw.y);
;                         if (kp == 0) rkdot[(size_t)m * 16 + h] = rkd;
;                         char* rec = scanrec + (rec0 + tok) * REC;
;                         *(f32x2*)(rec + kp * 8) = (f32x2){dec[0], dec[1]};
;                         *(f32x2*)(rec + 256 + kp * 8) = (f32x2){kkn[0], kkn[1]};
;                         *(f32x2*)(rec + 512 + kp * 8) = (f32x2){bb[0], bb[1]};
;                         *(unsigned*)(rec + 768 + kp * 4) = cvtpk(rr[0], rr[1]);
;                         *(unsigned*)(rec + 896 + kp * 4) = cvtpk(km[0], km[1]);
;                         *(unsigned*)(rec + 1024 + kp * 4) = cvtpk(vv[0], vv[1]);
;                         pr[0] = cr[0]; pr[1] = cr[1]; pk[0] = ck[0]; pk[1] = ck[1]; pv[0] = cv[0]; pv[1] = cv[1];
;                     }
.LBB0_424:
	s_or_b64 exec, exec, s[42:43]
	v_lshlrev_b32_e32 v18, 16, v97
	s_nop 0
	s_nop 0
	v_sub_f32_e32 v7, v12, v18
	v_fmac_f32_e32 v18, v48, v7
	v_add_f32_e32 v12, v46, v101
	v_add_f32_e32 v7, v47, v100
	v_mul_f32_e32 v12, 0xbfb8aa3b, v12
	v_mul_f32_e32 v7, 0xbfb8aa3b, v7
	v_exp_f32_e32 v12, v12
	v_exp_f32_e32 v7, v7
	v_and_b32_e32 v19, 0xffff0000, v97
	v_sub_f32_e32 v6, v6, v19
	v_fmac_f32_e32 v19, v49, v6
	v_add_f32_e32 v6, 1.0, v12
	v_add_f32_e32 v7, 1.0, v7
	s_waitcnt lgkmcnt(1)
	v_add_f32_e32 v12, v17, v20
	v_rcp_f32_e32 v6, v6
	v_rcp_f32_e32 v7, v7
	v_add_f32_e32 v12, 0x2b8cbccc, v12
	v_mul_f32_e32 v17, 0x4b800000, v12
	v_cmp_gt_f32_e32 vcc, s33, v12
	v_mul_f32_e32 v6, 0xbf1b4598, v6
	v_mul_f32_e32 v7, 0xbf1b4598, v7
	v_cndmask_b32_e32 v12, v12, v17, vcc
	v_rsq_f32_e32 v12, v12
	v_mul_f32_e32 v6, 0x3fb8aa3b, v6
	v_mul_f32_e32 v7, 0x3fb8aa3b, v7
	v_exp_f32_e32 v6, v6
	v_exp_f32_e32 v7, v7
	v_mul_f32_e32 v17, 0x45800000, v12
	v_cndmask_b32_e32 v12, v12, v17, vcc
	v_pk_mul_f32 v[4:5], v[4:5], v[12:13] op_sel_hi:[1,0]
	s_add_i32 s96, s96, s0
	v_pk_mul_f32 v[10:11], v[10:11], v[4:5]
	global_store_dwordx2 v[8:9], v[6:7], off offset:896
	global_store_dwordx2 v[8:9], v[4:5], off offset:1152
	global_store_dwordx2 v[8:9], v[10:11], off offset:1408
	v_add_co_u32_e32 v4, vcc, 0x4000, v32
	v_cvt_pk_bf16_f32 v6, v13, v14
	s_cmpk_gt_i32 s96, 0x41f
	s_nop 0
	v_addc_co_u32_e32 v5, vcc, 0, v33, vcc
	global_store_dword v[4:5], v6, off offset:1664
	v_cvt_pk_bf16_f32 v6, v15, v16
	global_store_dword v[4:5], v6, off offset:1792
	v_cvt_pk_bf16_f32 v6, v18, v19
	global_store_dword v[4:5], v6, off offset:1920
	s_cbranch_scc1 .LBB0_498

; __device__ __forceinline__ float bf2f(bf16_t b) { return __uint_as_float((unsigned)b << 16); }
; __device__ __forceinline__ unsigned cvtpk(float lo, float hi) { unsigned r; asm volatile("v_cvt_pk_bf16_f32 %0, %1, %2" : "=v"(r) : "v"(lo), "v"(hi)); return r; }
; __global__ void __launch_bounds__(NWAVES * 64, 2) mk_fwd(Args args) {
;     ...
;                 for (int tile = bx; tile < M / 16; tile += G) {
;                     const int m0 = tile * 16;
;                     const bool smp = m0 >= MP;
;                     const int b = smp ? ((m0 - MP) >> 5) : (m0 >> 12), t0 = smp ? ((m0 - MP) & 31) : (m0 & 4095);
;                     const bool first = t0 == 0;
;                     const float* shst = args.in[7] + (size_t)(l * DB + b) * SHIFT_DIM;
;                     const size_t rec0 = smp ? (size_t)SREC_S0 + (size_t)(b * 16 + h) * DS + t0 : (size_t)(b * 16 + h) * SEQ + t0;
;                     __syncthreads();
; #pragma unroll
;                     for (int e = 0; e < 4; ++e) { const int idx = tid + 512 * e, tok = idx >> 7, i = idx & 127, col = 3072 + i, m = m0 + tok;
;                         const float cur = bf2f(proj[(size_t)m * NPAD + col]);
;                         float prev;
;                         if (tok == 0 && first) prev = smp ? shst[col] : 0.f; else prev = bf2f(proj[(size_t)(m - 1) * NPAD + col]);
;                         float xsv = cur + (prev - cur) * mu[col];
;                         if (i < 64) { const float e2 = __expf(2.f * xsv); xsv = 1.f - 2.f * __builtin_amdgcn_rcpf(e2 + 1.f); }
;                         const float xo = __shfl_xor(xsv, 1);
;                         if (!(i & 1)) actP[(i >> 1) * 16 + tok] = cvtpk(xsv, xo); }
.LBB0_429:
	v_add_u32_e32 v4, s80, v55
	s_movk_i32 s56, 0x5e00
	v_mad_i64_i32 v[6:7], s[56:57], v4, s56, v[56:57]
	global_load_dword v9, v[58:59], off
	global_load_ushort v12, v[6:7], off
	s_mov_b64 s[56:57], 0x17800
	v_lshl_add_u64 v[10:11], v[6:7], 0, s[56:57]
	global_load_ushort v13, v[10:11], off
	s_mov_b64 s[56:57], 0x11a00
	v_lshl_add_u64 v[10:11], v[6:7], 0, s[56:57]
	global_load_ushort v17, v[10:11], off
	s_mov_b64 s[56:57], 0x2f000
	v_lshl_add_u64 v[10:11], v[6:7], 0, s[56:57]
	global_load_ushort v14, v[10:11], off
	s_mov_b64 s[56:57], 0x29200
	v_lshl_add_u64 v[10:11], v[6:7], 0, s[56:57]
	global_load_ushort v18, v[10:11], off
	s_mov_b64 s[56:57], 0x46800
	v_lshl_add_u64 v[10:11], v[6:7], 0, s[56:57]
	global_load_ushort v15, v[10:11], off
	s_mov_b64 s[56:57], 0x40a00
	v_lshl_add_u64 v[10:11], v[6:7], 0, s[56:57]
	global_load_ushort v19, v[10:11], off
	v_readfirstlane_b32 s92, v62
	v_readfirstlane_b32 s93, v63
	s_and_b64 s[56:57], s[42:43], exec
	s_cselect_b32 s58, s59, s58
	s_cselect_b32 s59, s60, s61
	s_cmp_eq_u32 s59, 0
	s_cselect_b64 s[56:57], -1, 0
	s_cmp_lg_u32 s59, 0
	s_cselect_b64 s[88:89], -1, 0
	s_add_i32 s58, s58, s19
	s_mul_hi_i32 s59, s58, 0x3200
	s_mulk_i32 s58, 0x3200
	v_readlane_b32 s74, v252, 50
	v_readlane_b32 s75, v252, 51
	s_nop 3
	s_add_u32 s84, s74, s58
	s_addc_u32 s85, s75, s59
	s_and_b64 s[58:59], s[8:9], s[56:57]
	s_xor_b64 s[58:59], s[58:59], -1
	s_and_saveexec_b64 s[60:61], s[58:59]
	s_xor_b64 s[58:59], exec, s[60:61]
	s_cbranch_execz .LBB0_431
	v_add_u32_e32 v4, -1, v4
	s_movk_i32 s60, 0x5e00
	v_mad_i64_i32 v[4:5], s[60:61], v4, s60, v[56:57]
	global_load_ushort v16, v[4:5], off

; __device__ __forceinline__ float bf2f(bf16_t b) { return __uint_as_float((unsigned)b << 16); }
; __device__ __forceinline__ unsigned cvtpk(float lo, float hi) { unsigned r; asm volatile("v_cvt_pk_bf16_f32 %0, %1, %2" : "=v"(r) : "v"(lo), "v"(hi)); return r; }
; __global__ void __launch_bounds__(NWAVES * 64, 2) mk_fwd(Args args) {
;     ...
;                     for (int e = 0; e < 4; ++e) { const int idx = tid + 512 * e, tok = idx >> 7, i = idx & 127, col = 3072 + i, m = m0 + tok;
;                         const float cur = bf2f(proj[(size_t)m * NPAD + col]);
;                         float prev;
;                         if (tok == 0 && first) prev = smp ? shst[col] : 0.f; else prev = bf2f(proj[(size_t)(m - 1) * NPAD + col]);
;                         float xsv = cur + (prev - cur) * mu[col];
;                         if (i < 64) { const float e2 = __expf(2.f * xsv); xsv = 1.f - 2.f * __builtin_amdgcn_rcpf(e2 + 1.f); }
;                         const float xo = __shfl_xor(xsv, 1);
;                         if (!(i & 1)) actP[(i >> 1) * 16 + tok] = cvtpk(xsv, xo); }
;                     __syncthreads();
;                     unsigned pur[17], puk[17], puv[17];
; #pragma unroll
;                     for (int tok = 0; tok < 17; ++tok) { if (tok == 0 && first) { pur[0] = puk[0] = puv[0] = 0u; continue; }
;                         const bf16_t* pp = proj + (size_t)(m0 + tok - 1) * NPAD + c0; pur[tok] = *(const unsigned*)pp; puk[tok] = *(const unsigned*)(pp + RW); puv[tok] = *(const unsigned*)(pp + 2 * RW); }
;                     float lw[16][2], la[16][2];
; #pragma unroll
;                     for (int t = 0; t < 16; ++t) { lw[t][0] = 0.f; lw[t][1] = 0.f; la[t][0] = 0.f; la[t][1] = 0.f; }
;                     u32x2 wvn = *(const u32x2*)(w2pl + c0), avn = *(const u32x2*)(w2pl + (size_t)32 * RW + c0);
;                     for (int ip = 0; ip < 32; ++ip) {
;                         const u32x2 wv = wvn, av = avn;
;                         { const int ipn = ip < 31 ? ip + 1 : 31; wvn = *(const u32x2*)(w2pl + (size_t)ipn * RW + c0); avn = *(const u32x2*)(w2pl + (size_t)(32 + ipn) * RW + c0); }
.LBB0_434:
	s_or_b64 exec, exec, s[58:59]
	v_and_b32_e32 v248, 15, v109
	v_bfe_u32 v20, v109, 4, 2
	v_lshlrev_b32_e32 v248, 4, v248
	v_lshl_or_b32 v248, v20, 14, v248
	s_mov_b64 s[94:95], s[92:93]
	global_load_dwordx4 v[128:131], v248, s[94:95]
	s_add_u32 s94, s92, 0x1000
	s_addc_u32 s95, s93, 0
	global_load_dwordx4 v[132:135], v248, s[94:95]
	s_add_u32 s94, s92, 0x2000
	s_addc_u32 s95, s93, 0
	global_load_dwordx4 v[136:139], v248, s[94:95]
	s_add_u32 s94, s92, 0x3000
	s_addc_u32 s95, s93, 0
	global_load_dwordx4 v[140:143], v248, s[94:95]
	s_add_u32 s94, s92, 0x10000
	s_addc_u32 s95, s93, 0
	global_load_dwordx4 v[144:147], v248, s[94:95]
	s_add_u32 s94, s92, 0x11000
	s_addc_u32 s95, s93, 0
	global_load_dwordx4 v[148:151], v248, s[94:95]
	s_add_u32 s94, s92, 0x12000
	s_addc_u32 s95, s93, 0
	global_load_dwordx4 v[152:155], v248, s[94:95]
	s_add_u32 s94, s92, 0x13000
	s_addc_u32 s95, s93, 0
	global_load_dwordx4 v[156:159], v248, s[94:95]
	s_mov_b64 s[94:95], s[92:93]
	global_load_dwordx4 v[160:163], v248, s[94:95] offset:256
	s_add_u32 s94, s92, 0x1000
	s_addc_u32 s95, s93, 0
	global_load_dwordx4 v[172:175], v248, s[94:95] offset:256
	s_add_u32 s94, s92, 0x2000
	s_addc_u32 s95, s93, 0
	global_load_dwordx4 v[176:179], v248, s[94:95] offset:256
	s_add_u32 s94, s92, 0x3000
	s_addc_u32 s95, s93, 0
	global_load_dwordx4 v[180:183], v248, s[94:95] offset:256
	s_add_u32 s94, s92, 0x10000
	s_addc_u32 s95, s93, 0
	global_load_dwordx4 v[184:187], v248, s[94:95] offset:256
	s_add_u32 s94, s92, 0x11000
	s_addc_u32 s95, s93, 0
	global_load_dwordx4 v[208:211], v248, s[94:95] offset:256
	s_add_u32 s94, s92, 0x12000
	s_addc_u32 s95, s93, 0
	global_load_dwordx4 v[212:215], v248, s[94:95] offset:256
	s_add_u32 s94, s92, 0x13000
	s_addc_u32 s95, s93, 0
	global_load_dwordx4 v[216:219], v248, s[94:95] offset:256
	s_add_u32 s94, s92, 0x20000
	s_addc_u32 s95, s93, 0
	global_load_dwordx4 v[220:223], v248, s[94:95]
	s_add_u32 s94, s92, 0x21000
	s_addc_u32 s95, s93, 0
	global_load_dwordx4 v[228:231], v248, s[94:95]
	s_add_u32 s94, s92, 0x22000
	s_addc_u32 s95, s93, 0
	global_load_dwordx4 v[232:235], v248, s[94:95]
	s_add_u32 s94, s92, 0x23000
	s_addc_u32 s95, s93, 0
	global_load_dwordx4 v[240:243], v248, s[94:95]
	s_add_u32 s94, s92, 0x30000
	s_addc_u32 s95, s93, 0
	global_load_dwordx4 v[244:247], v248, s[94:95]
	s_add_u32 s94, s92, 0x31000
	s_addc_u32 s95, s93, 0
	global_load_dwordx4 v[74:77], v248, s[94:95]
	s_add_u32 s94, s92, 0x32000
	s_addc_u32 s95, s93, 0
	global_load_dwordx4 v[120:123], v248, s[94:95]
	s_add_u32 s94, s92, 0x33000
	s_addc_u32 s95, s93, 0
	global_load_dwordx4 v[28:31], v248, s[94:95]
	v_and_b32_e32 v20, 0x7e, v109
	v_lshlrev_b32_e32 v20, 1, v20
	v_mul_u32_u24_e32 v8, 0x110, v55
	v_add_u32_e32 v20, v20, v8
	v_add_u32_e32 v20, 0x22400, v20
	s_waitcnt vmcnt(24)
	s_barrier
	v_lshlrev_b32_e32 v16, 16, v16
	v_cndmask_b32_e64 v16, v7, v16, s[58:59]
	v_lshlrev_b32_e32 v17, 16, v17
	v_lshlrev_b32_e32 v18, 16, v18
	v_lshlrev_b32_e32 v19, 16, v19
	v_lshlrev_b32_e32 v12, 16, v12
	v_lshlrev_b32_e32 v13, 16, v13
	v_lshlrev_b32_e32 v14, 16, v14
	v_lshlrev_b32_e32 v15, 16, v15
	v_sub_f32_e32 v16, v16, v12
	v_sub_f32_e32 v17, v17, v13
	v_sub_f32_e32 v18, v18, v14
	v_sub_f32_e32 v19, v19, v15
	v_fmac_f32_e32 v12, v16, v9
	v_fmac_f32_e32 v13, v17, v9
	v_fmac_f32_e32 v14, v18, v9
	v_fmac_f32_e32 v15, v19, v9
	v_add_f32_e32 v16, v12, v12
	v_add_f32_e32 v17, v13, v13
	v_add_f32_e32 v18, v14, v14
	v_add_f32_e32 v19, v15, v15
	v_mul_f32_e32 v16, 0x3fb8aa3b, v16
	v_mul_f32_e32 v17, 0x3fb8aa3b, v17
	v_mul_f32_e32 v18, 0x3fb8aa3b, v18
	v_mul_f32_e32 v19, 0x3fb8aa3b, v19
	v_exp_f32_e32 v16, v16
	v_exp_f32_e32 v17, v17
	v_exp_f32_e32 v18, v18
	v_exp_f32_e32 v19, v19
	s_nop 0
	v_add_f32_e32 v16, 1.0, v16
	v_add_f32_e32 v17, 1.0, v17
	v_add_f32_e32 v18, 1.0, v18
	v_add_f32_e32 v19, 1.0, v19
	v_rcp_f32_e32 v16, v16
	v_rcp_f32_e32 v17, v17
	v_rcp_f32_e32 v18, v18
	v_rcp_f32_e32 v19, v19
	s_nop 0
	v_fma_f32 v16, v16, -2.0, 1.0
	v_fma_f32 v17, v17, -2.0, 1.0
	v_fma_f32 v18, v18, -2.0, 1.0
	v_fma_f32 v19, v19, -2.0, 1.0
	v_cndmask_b32_e64 v12, v12, v16, s[2:3]
	v_cndmask_b32_e64 v13, v13, v17, s[2:3]
	v_cndmask_b32_e64 v14, v14, v18, s[2:3]
	v_cndmask_b32_e64 v15, v15, v19, s[2:3]
	ds_bpermute_b32 v16, v88, v12
	ds_bpermute_b32 v17, v88, v13
	ds_bpermute_b32 v18, v88, v14
	ds_bpermute_b32 v19, v88, v15
	s_and_saveexec_b64 s[56:57], s[4:5]
	s_waitcnt lgkmcnt(0)
	v_cvt_pk_bf16_f32 v12, v12, v16
	ds_write_b32 v20, v12 offset:0
	v_cvt_pk_bf16_f32 v13, v13, v17
	ds_write_b32 v20, v13 offset:1088
	v_cvt_pk_bf16_f32 v14, v14, v18
	ds_write_b32 v20, v14 offset:2176
	v_cvt_pk_bf16_f32 v15, v15, v19
	ds_write_b32 v20, v15 offset:3264
; #define LAS __attribute__((address_space(3)))
; #define DOT2(a_, b_, c_) __builtin_amdgcn_fdot2_f32_bf16(__builtin_bit_cast(bf16x2_t, (unsigned)(a_)), __builtin_bit_cast(bf16x2_t, (unsigned)(b_)), (c_), false)
; __global__ void __launch_bounds__(NWAVES * 64, 2) mk_fwd(Args args) {
;     ...
;                     __syncthreads();
;                     unsigned pur[17], puk[17], puv[17];
; #pragma unroll
;                     for (int tok = 0; tok < 17; ++tok) { if (tok == 0 && first) { pur[0] = puk[0] = puv[0] = 0u; continue; }
;                         const bf16_t* pp = proj + (size_t)(m0 + tok - 1) * NPAD + c0; pur[tok] = *(const unsigned*)pp; puk[tok] = *(const unsigned*)(pp + RW); puv[tok] = *(const unsigned*)(pp + 2 * RW); }
;                     float lw[16][2], la[16][2];
; #pragma unroll
;                     for (int t = 0; t < 16; ++t) { lw[t][0] = 0.f; lw[t][1] = 0.f; la[t][0] = 0.f; la[t][1] = 0.f; }
;                     u32x2 wvn = *(const u32x2*)(w2pl + c0), avn = *(const u32x2*)(w2pl + (size_t)32 * RW + c0);
;                     for (int ip = 0; ip < 32; ++ip) {
;                         const u32x2 wv = wvn, av = avn;
;                         { const int ipn = ip < 31 ? ip + 1 : 31; wvn = *(const u32x2*)(w2pl + (size_t)ipn * RW + c0); avn = *(const u32x2*)(w2pl + (size_t)(32 + ipn) * RW + c0); }
; #pragma unroll
;                         for (int tq = 0; tq < 4; ++tq) { const u32x4 x4 = *(LAS const u32x4*)(actP + ip * 16 + tq * 4), y4 = *(LAS const u32x4*)(actP + (32 + ip) * 16 + tq * 4);
; #pragma unroll
;                             for (int e = 0; e < 4; ++e) { lw[tq * 4 + e][0] = DOT2(x4[e], wv.x, lw[tq * 4 + e][0]); lw[tq * 4 + e][1] = DOT2(x4[e], wv.y, lw[tq * 4 + e][1]);
;                                                           la[tq * 4 + e][0] = DOT2(y4[e], av.x, la[tq * 4 + e][0]); la[tq * 4 + e][1] = DOT2(y4[e], av.y, la[tq * 4 + e][1]); } }
;                     }
.LBB0_457:
	s_or_b64 exec, exec, s[56:57]
	s_waitcnt lgkmcnt(0)
	s_barrier
	v_and_b32_e32 v249, 15, v109
	v_mul_u32_u24_e32 v249, 0x110, v249
	v_bfe_u32 v164, v109, 4, 2
	v_lshl_add_u32 v249, v164, 4, v249
	v_add_u32_e32 v249, 0x22400, v249
	ds_read_b128 v[20:23], v249 offset:0
	ds_read_b128 v[24:27], v249 offset:64
	v_lshrrev_b32_e32 v164, 6, v109
	v_lshl_add_u32 v164, v164, 9, v248
	v_add_u32_e32 v165, 0x10000, v164
	v_lshlrev_b32_e32 v194, 3, v109
	v_add_u32_e32 v195, 0x10000, v194
	s_waitcnt vmcnt(16)
	v_swap_b32 v129, v132
	v_swap_b32 v130, v136
	v_swap_b32 v131, v140
	v_swap_b32 v134, v137
	v_swap_b32 v135, v141
	v_swap_b32 v139, v142
	v_swap_b32 v145, v148
	v_swap_b32 v146, v152
	v_swap_b32 v147, v156
	v_swap_b32 v150, v153
	v_swap_b32 v151, v157
	v_swap_b32 v155, v158
	s_waitcnt lgkmcnt(0)
	s_nop 1
	v_mfma_f32_16x16x32_bf16 v[4:7], v[20:23], v[128:131], 0
	v_mfma_f32_16x16x32_bf16 v[8:11], v[20:23], v[132:135], 0
	v_mfma_f32_16x16x32_bf16 v[12:15], v[20:23], v[136:139], 0
	v_mfma_f32_16x16x32_bf16 v[16:19], v[20:23], v[140:143], 0
	v_mfma_f32_16x16x32_bf16 v[4:7], v[24:27], v[144:147], v[4:7]
	v_mfma_f32_16x16x32_bf16 v[8:11], v[24:27], v[148:151], v[8:11]
	v_mfma_f32_16x16x32_bf16 v[12:15], v[24:27], v[152:155], v[12:15]
	v_mfma_f32_16x16x32_bf16 v[16:19], v[24:27], v[156:159], v[16:19]
	s_add_u32 s94, s92, 0x20000
	s_addc_u32 s95, s93, 0
	global_load_dwordx4 v[128:131], v248, s[94:95] offset:256
	s_add_u32 s94, s92, 0x21000
	s_addc_u32 s95, s93, 0
	global_load_dwordx4 v[132:135], v248, s[94:95] offset:256
	s_add_u32 s94, s92, 0x22000
	s_addc_u32 s95, s93, 0
	global_load_dwordx4 v[136:139], v248, s[94:95] offset:256
	s_add_u32 s94, s92, 0x23000
	s_addc_u32 s95, s93, 0
	global_load_dwordx4 v[140:143], v248, s[94:95] offset:256
	s_add_u32 s94, s92, 0x30000
	s_addc_u32 s95, s93, 0
	global_load_dwordx4 v[144:147], v248, s[94:95] offset:256
	s_add_u32 s94, s92, 0x31000
	s_addc_u32 s95, s93, 0
	global_load_dwordx4 v[148:151], v248, s[94:95] offset:256
	s_add_u32 s94, s92, 0x32000
	s_addc_u32 s95, s93, 0
	global_load_dwordx4 v[152:155], v248, s[94:95] offset:256
	s_add_u32 s94, s92, 0x33000
	s_addc_u32 s95, s93, 0
	global_load_dwordx4 v[156:159], v248, s[94:95] offset:256
	s_waitcnt vmcnt(16)
	v_swap_b32 v161, v172
	v_swap_b32 v162, v176
	v_swap_b32 v163, v180
	v_swap_b32 v174, v177
	v_swap_b32 v175, v181
	v_swap_b32 v179, v182
	v_swap_b32 v185, v208
	v_swap_b32 v186, v212
	v_swap_b32 v187, v216
	v_swap_b32 v210, v213
	v_swap_b32 v211, v217
	v_swap_b32 v215, v218
	s_nop 1
	v_mfma_f32_16x16x32_bf16 v[100:103], v[20:23], v[160:163], 0
	v_mfma_f32_16x16x32_bf16 v[104:107], v[20:23], v[172:175], 0
	v_mfma_f32_16x16x32_bf16 v[112:115], v[20:23], v[176:179], 0
	v_mfma_f32_16x16x32_bf16 v[116:119], v[20:23], v[180:183], 0
	v_mfma_f32_16x16x32_bf16 v[100:103], v[24:27], v[184:187], v[100:103]
	v_mfma_f32_16x16x32_bf16 v[104:107], v[24:27], v[208:211], v[104:107]
	v_mfma_f32_16x16x32_bf16 v[112:115], v[24:27], v[212:215], v[112:115]
	v_mfma_f32_16x16x32_bf16 v[116:119], v[24:27], v[216:219], v[116:119]
	ds_read_b128 v[20:23], v249 offset:128
	ds_read_b128 v[24:27], v249 offset:192
	v_swap_b32 v5, v8
	v_swap_b32 v6, v12
	v_swap_b32 v7, v16
	v_swap_b32 v10, v13
	v_swap_b32 v11, v17
	v_swap_b32 v15, v18
	ds_write_b128 v164, v[4:7] offset:0
	ds_write_b128 v164, v[8:11] offset:4096
	ds_write_b128 v164, v[12:15] offset:8192
	ds_write_b128 v164, v[16:19] offset:12288
	s_waitcnt vmcnt(8)
	v_swap_b32 v221, v228
	v_swap_b32 v222, v232
	v_swap_b32 v223, v240
	v_swap_b32 v230, v233
	v_swap_b32 v231, v241
	v_swap_b32 v235, v242
	v_swap_b32 v245, v74
	v_swap_b32 v246, v120
	v_swap_b32 v247, v28
	v_swap_b32 v76, v121
	v_swap_b32 v77, v29
	v_swap_b32 v123, v30
	s_waitcnt lgkmcnt(4)
	s_nop 1
	v_mfma_f32_16x16x32_bf16 v[4:7], v[20:23], v[220:223], 0
	v_mfma_f32_16x16x32_bf16 v[8:11], v[20:23], v[228:231], 0
	v_mfma_f32_16x16x32_bf16 v[12:15], v[20:23], v[232:235], 0
	v_mfma_f32_16x16x32_bf16 v[16:19], v[20:23], v[240:243], 0
	v_mfma_f32_16x16x32_bf16 v[4:7], v[24:27], v[244:247], v[4:7]
	v_mfma_f32_16x16x32_bf16 v[8:11], v[24:27], v[74:77], v[8:11]
	v_mfma_f32_16x16x32_bf16 v[12:15], v[24:27], v[120:123], v[12:15]
	v_mfma_f32_16x16x32_bf16 v[16:19], v[24:27], v[28:31], v[16:19]
	v_swap_b32 v101, v104
	v_swap_b32 v102, v112
	v_swap_b32 v103, v116
	v_swap_b32 v106, v113
	v_swap_b32 v107, v117
	v_swap_b32 v115, v118
	ds_write_b128 v164, v[100:103] offset:256
	ds_write_b128 v164, v[104:107] offset:4352
	ds_write_b128 v164, v[112:115] offset:8448
	ds_write_b128 v164, v[116:119] offset:12544
	s_waitcnt vmcnt(0)
	v_swap_b32 v129, v132
	v_swap_b32 v130, v136
	v_swap_b32 v131, v140
	v_swap_b32 v134, v137
	v_swap_b32 v135, v141
	v_swap_b32 v139, v142
	v_swap_b32 v145, v148
	v_swap_b32 v146, v152
	v_swap_b32 v147, v156
	v_swap_b32 v150, v153
	v_swap_b32 v151, v157
	v_swap_b32 v155, v158
	s_nop 1
	v_mfma_f32_16x16x32_bf16 v[100:103], v[20:23], v[128:131], 0
	v_mfma_f32_16x16x32_bf16 v[104:107], v[20:23], v[132:135], 0
	v_mfma_f32_16x16x32_bf16 v[112:115], v[20:23], v[136:139], 0
	v_mfma_f32_16x16x32_bf16 v[116:119], v[20:23], v[140:143], 0
	v_mfma_f32_16x16x32_bf16 v[100:103], v[24:27], v[144:147], v[100:103]
	v_mfma_f32_16x16x32_bf16 v[104:107], v[24:27], v[148:151], v[104:107]
	v_mfma_f32_16x16x32_bf16 v[112:115], v[24:27], v[152:155], v[112:115]
	v_mfma_f32_16x16x32_bf16 v[116:119], v[24:27], v[156:159], v[116:119]
	v_swap_b32 v5, v8
	v_swap_b32 v6, v12
	v_swap_b32 v7, v16
	v_swap_b32 v10, v13
	v_swap_b32 v11, v17
	v_swap_b32 v15, v18
	ds_write_b128 v165, v[4:7] offset:0
	ds_write_b128 v165, v[8:11] offset:4096
	ds_write_b128 v165, v[12:15] offset:8192
	ds_write_b128 v165, v[16:19] offset:12288
	s_nop 7
	v_swap_b32 v101, v104
	v_swap_b32 v102, v112
	v_swap_b32 v103, v116
	v_swap_b32 v106, v113
	v_swap_b32 v107, v117
	v_swap_b32 v115, v118
	ds_write_b128 v165, v[100:103] offset:256
	ds_write_b128 v165, v[104:107] offset:4352
	ds_write_b128 v165, v[112:115] offset:8448
	ds_write_b128 v165, v[116:119] offset:12544
	v_mov_b32_e32 v122, 0
	v_mov_b32_e32 v227, 0
	v_mov_b32_e32 v80, 0
	v_mov_b32_e32 v81, 0
	s_andn2_b64 vcc, exec, s[88:89]
	s_cbranch_vccnz .LBB0_459
	s_add_i32 s56, s80, -1
	v_mad_i64_i32 v[4:5], s[56:57], s56, v198, v[60:61]
	global_load_dword v81, v[4:5], off
	global_load_dword v80, v[4:5], off offset:2048
	v_add_co_u32_e32 v4, vcc, 0x1000, v4
	s_nop 1
	v_addc_co_u32_e32 v5, vcc, 0, v5, vcc
	global_load_dword v227, v[4:5], off
; #define LAS __attribute__((address_space(3)))
; #define DOT2(a_, b_, c_) __builtin_amdgcn_fdot2_f32_bf16(__builtin_bit_cast(bf16x2_t, (unsigned)(a_)), __builtin_bit_cast(bf16x2_t, (unsigned)(b_)), (c_), false)
; __global__ void __launch_bounds__(NWAVES * 64, 2) mk_fwd(Args args) {
;     ...
;                     unsigned pur[17], puk[17], puv[17];
; #pragma unroll
;                     for (int tok = 0; tok < 17; ++tok) { if (tok == 0 && first) { pur[0] = puk[0] = puv[0] = 0u; continue; }
;                         const bf16_t* pp = proj + (size_t)(m0 + tok - 1) * NPAD + c0; pur[tok] = *(const unsigned*)pp; puk[tok] = *(const unsigned*)(pp + RW); puv[tok] = *(const unsigned*)(pp + 2 * RW); }
;                     float lw[16][2], la[16][2];
; #pragma unroll
;                     for (int t = 0; t < 16; ++t) { lw[t][0] = 0.f; lw[t][1] = 0.f; la[t][0] = 0.f; la[t][1] = 0.f; }
;                     u32x2 wvn = *(const u32x2*)(w2pl + c0), avn = *(const u32x2*)(w2pl + (size_t)32 * RW + c0);
;                     for (int ip = 0; ip < 32; ++ip) {
;                         const u32x2 wv = wvn, av = avn;
;                         { const int ipn = ip < 31 ? ip + 1 : 31; wvn = *(const u32x2*)(w2pl + (size_t)ipn * RW + c0); avn = *(const u32x2*)(w2pl + (size_t)(32 + ipn) * RW + c0); }
; #pragma unroll
;                         for (int tq = 0; tq < 4; ++tq) { const u32x4 x4 = *(LAS const u32x4*)(actP + ip * 16 + tq * 4), y4 = *(LAS const u32x4*)(actP + (32 + ip) * 16 + tq * 4);
; #pragma unroll
;                             for (int e = 0; e < 4; ++e) { lw[tq * 4 + e][0] = DOT2(x4[e], wv.x, lw[tq * 4 + e][0]); lw[tq * 4 + e][1] = DOT2(x4[e], wv.y, lw[tq * 4 + e][1]);
;                                                           la[tq * 4 + e][0] = DOT2(y4[e], av.x, la[tq * 4 + e][0]); la[tq * 4 + e][1] = DOT2(y4[e], av.y, la[tq * 4 + e][1]); } }
;                     }
.LBB0_459:
	v_mad_i64_i32 v[4:5], s[56:57], s80, v198, v[60:61]
	v_add_co_u32_e32 v6, vcc, 0x1000, v4
	s_or_b32 s90, s80, 1
	s_nop 0
	v_addc_co_u32_e32 v7, vcc, 0, v5, vcc
	v_mad_i64_i32 v[8:9], s[56:57], s90, v198, v[60:61]
	v_add_co_u32_e32 v10, vcc, 0x1000, v8
	s_or_b32 s86, s80, 2
	s_nop 0
	v_addc_co_u32_e32 v11, vcc, 0, v9, vcc
	v_mad_i64_i32 v[12:13], s[56:57], s86, v198, v[60:61]
	v_add_co_u32_e32 v14, vcc, 0x1000, v12
	s_or_b32 s82, s80, 3
	s_nop 0
	v_addc_co_u32_e32 v15, vcc, 0, v13, vcc
	v_mad_i64_i32 v[16:17], s[56:57], s82, v198, v[60:61]
	global_load_dword v224, v[6:7], off
	global_load_dword v221, v[8:9], off
	global_load_dword v220, v[8:9], off offset:2048
	global_load_dword v216, v[10:11], off
	global_load_dword v214, v[12:13], off
	global_load_dword v213, v[12:13], off offset:2048
	global_load_dword v210, v[14:15], off
	global_load_dword v206, v[16:17], off
	v_add_co_u32_e32 v6, vcc, 0x1000, v16
	s_or_b32 s78, s80, 4
	s_nop 0
	v_addc_co_u32_e32 v7, vcc, 0, v17, vcc
	v_mad_i64_i32 v[8:9], s[56:57], s78, v198, v[60:61]
	v_add_co_u32_e32 v10, vcc, 0x1000, v8
	s_or_b32 s76, s80, 5
	s_nop 0
	v_addc_co_u32_e32 v11, vcc, 0, v9, vcc
	v_mad_i64_i32 v[12:13], s[56:57], s76, v198, v[60:61]
	v_add_co_u32_e32 v14, vcc, 0x1000, v12
	s_or_b32 s74, s80, 6
	s_nop 0
	v_addc_co_u32_e32 v15, vcc, 0, v13, vcc
	global_load_dword v207, v[16:17], off offset:2048
	global_load_dword v187, v[6:7], off
	global_load_dword v182, v[8:9], off
	global_load_dword v181, v[8:9], off offset:2048
	global_load_dword v180, v[10:11], off
	global_load_dword v175, v[12:13], off
	global_load_dword v174, v[12:13], off offset:2048
	global_load_dword v173, v[14:15], off
	v_mad_i64_i32 v[6:7], s[56:57], s74, v198, v[60:61]
	v_add_co_u32_e32 v8, vcc, 0x1000, v6
	s_or_b32 s72, s80, 7
	s_nop 0
	v_addc_co_u32_e32 v9, vcc, 0, v7, vcc
	v_mad_i64_i32 v[10:11], s[56:57], s72, v198, v[60:61]
	v_add_co_u32_e32 v12, vcc, 0x1000, v10
	s_or_b32 s70, s80, 8
	s_nop 0
	v_addc_co_u32_e32 v13, vcc, 0, v11, vcc
	v_mad_i64_i32 v[14:15], s[56:57], s70, v198, v[60:61]
	global_load_dword v162, v[6:7], off
	global_load_dword v161, v[6:7], off offset:2048
	global_load_dword v158, v[8:9], off
	global_load_dword v156, v[10:11], off
	global_load_dword v155, v[10:11], off offset:2048
	global_load_dword v151, v[12:13], off
	global_load_dword v148, v[14:15], off
	global_load_dword v147, v[14:15], off offset:2048
	v_add_co_u32_e32 v6, vcc, 0x1000, v14
	s_or_b32 s68, s80, 9
	s_nop 0
	v_addc_co_u32_e32 v7, vcc, 0, v15, vcc
	v_mad_i64_i32 v[8:9], s[56:57], s68, v198, v[60:61]
	v_add_co_u32_e32 v10, vcc, 0x1000, v8
	s_or_b32 s66, s80, 10
	s_nop 0
	v_addc_co_u32_e32 v11, vcc, 0, v9, vcc
	v_mad_i64_i32 v[12:13], s[56:57], s66, v198, v[60:61]
	v_add_co_u32_e32 v14, vcc, 0x1000, v12
	s_or_b32 s64, s80, 11
	s_nop 0
	v_addc_co_u32_e32 v15, vcc, 0, v13, vcc
	v_mad_i64_i32 v[16:17], s[56:57], s64, v198, v[60:61]
	global_load_dword v144, v[6:7], off
	global_load_dword v143, v[8:9], off
	global_load_dword v142, v[8:9], off offset:2048
	global_load_dword v138, v[10:11], off
	global_load_dword v137, v[12:13], off
	global_load_dword v136, v[12:13], off offset:2048
	global_load_dword v131, v[14:15], off
	global_load_dword v129, v[16:17], off
	v_add_co_u32_e32 v6, vcc, 0x1000, v16
	s_or_b32 s62, s80, 12
	s_nop 0
	v_addc_co_u32_e32 v7, vcc, 0, v17, vcc
	v_mad_i64_i32 v[8:9], s[56:57], s62, v198, v[60:61]
	v_add_co_u32_e32 v10, vcc, 0x1000, v8
	s_or_b32 s60, s80, 13
	s_nop 0
	v_addc_co_u32_e32 v11, vcc, 0, v9, vcc
	v_mad_i64_i32 v[12:13], s[56:57], s60, v198, v[60:61]
	v_add_co_u32_e32 v14, vcc, 0x1000, v12
	s_or_b32 s58, s80, 14
	s_nop 0
	v_addc_co_u32_e32 v15, vcc, 0, v13, vcc
	global_load_dword v130, v[16:17], off offset:2048
	global_load_dword v125, v[6:7], off
	global_load_dword v121, v[8:9], off
	global_load_dword v120, v[8:9], off offset:2048
	global_load_dword v117, v[10:11], off
	global_load_dword v114, v[12:13], off
	global_load_dword v113, v[12:13], off offset:2048
	global_load_dword v110, v[14:15], off
	v_mad_i64_i32 v[6:7], s[56:57], s58, v198, v[60:61]
	v_add_co_u32_e32 v8, vcc, 0x1000, v6
	s_or_b32 s56, s80, 15
	s_nop 0
	v_addc_co_u32_e32 v9, vcc, 0, v7, vcc
	v_mad_i64_i32 v[10:11], vcc, s56, v198, v[60:61]
	v_add_co_u32_e32 v12, vcc, 0x1000, v10
	s_ashr_i32 s81, s80, 31
	s_nop 0
	v_addc_co_u32_e32 v13, vcc, 0, v11, vcc
	global_load_dword v106, v[6:7], off
	global_load_dword v105, v[6:7], off offset:2048
	global_load_dword v104, v[8:9], off
	global_load_dword v99, v[10:11], off
	global_load_dword v98, v[10:11], off offset:2048
	global_load_dword v97, v[12:13], off
	global_load_dword v235, v[4:5], off
	global_load_dword v234, v[4:5], off offset:2048
	s_ashr_i32 s91, s90, 31
	s_ashr_i32 s87, s86, 31
	s_ashr_i32 s83, s82, 31
	s_ashr_i32 s79, s78, 31
	s_ashr_i32 s77, s76, 31
	s_ashr_i32 s75, s74, 31
	s_ashr_i32 s73, s72, 31
	s_ashr_i32 s71, s70, 31
	s_ashr_i32 s69, s68, 31
	s_ashr_i32 s67, s66, 31
	s_ashr_i32 s65, s64, 31
	s_ashr_i32 s63, s62, 31
	s_ashr_i32 s61, s60, 31
	s_ashr_i32 s59, s58, 31
	s_ashr_i32 s57, s56, 31
	s_waitcnt lgkmcnt(0)
	s_barrier
; #define LAS __attribute__((address_space(3)))
; __device__ __forceinline__ float bflo(unsigned u) { return __uint_as_float(u << 16); }
; __device__ __forceinline__ float bfhi(unsigned u) { return __uint_as_float(u & 0xffff0000u); }
; #define DOT2(a_, b_, c_) __builtin_amdgcn_fdot2_f32_bf16(__builtin_bit_cast(bf16x2_t, (unsigned)(a_)), __builtin_bit_cast(bf16x2_t, (unsigned)(b_)), (c_), false)
; __global__ void __launch_bounds__(NWAVES * 64, 2) mk_fwd(Args args) {
;     ...
;                     float lw[16][2], la[16][2];
; #pragma unroll
;                     for (int t = 0; t < 16; ++t) { lw[t][0] = 0.f; lw[t][1] = 0.f; la[t][0] = 0.f; la[t][1] = 0.f; }
;                     u32x2 wvn = *(const u32x2*)(w2pl + c0), avn = *(const u32x2*)(w2pl + (size_t)32 * RW + c0);
;                     for (int ip = 0; ip < 32; ++ip) {
;                         const u32x2 wv = wvn, av = avn;
;                         { const int ipn = ip < 31 ? ip + 1 : 31; wvn = *(const u32x2*)(w2pl + (size_t)ipn * RW + c0); avn = *(const u32x2*)(w2pl + (size_t)(32 + ipn) * RW + c0); }
; #pragma unroll
;                         for (int tq = 0; tq < 4; ++tq) { const u32x4 x4 = *(LAS const u32x4*)(actP + ip * 16 + tq * 4), y4 = *(LAS const u32x4*)(actP + (32 + ip) * 16 + tq * 4);
; #pragma unroll
;                             for (int e = 0; e < 4; ++e) { lw[tq * 4 + e][0] = DOT2(x4[e], wv.x, lw[tq * 4 + e][0]); lw[tq * 4 + e][1] = DOT2(x4[e], wv.y, lw[tq * 4 + e][1]);
;                                                           la[tq * 4 + e][0] = DOT2(y4[e], av.x, la[tq * 4 + e][0]); la[tq * 4 + e][1] = DOT2(y4[e], av.y, la[tq * 4 + e][1]); } }
;                     }
;                     float pr[2], pk[2], pv[2];
;                     if (first) { if (smp) { pr[0] = shst[c0]; pr[1] = shst[c0 + 1]; pk[0] = shst[RW + c0]; pk[1] = shst[RW + c0 + 1]; pv[0] = shst[2 * RW + c0]; pv[1] = shst[2 * RW + c0 + 1]; }
;                                  else { pr[0] = pr[1] = pk[0] = pk[1] = pv[0] = pv[1] = 0.f; } }
;                     else { const unsigned ur = pur[0], uk = puk[0], uv = puv[0];
;                            pr[0] = bflo(ur); pr[1] = bfhi(ur); pk[0] = bflo(uk); pk[1] = bfhi(uk); pv[0] = bflo(uv); pv[1] = bfhi(uv); }
	ds_read_b32 v233, v194 offset:0
	ds_read_b32 v232, v194 offset:4
	ds_read_b32 v229, v194 offset:4096
	ds_read_b32 v228, v194 offset:4100
	ds_read_b32 v223, v194 offset:8192
	ds_read_b32 v222, v194 offset:8196
	ds_read_b32 v217, v194 offset:12288
	ds_read_b32 v215, v194 offset:12292
	ds_read_b32 v209, v194 offset:16384
	ds_read_b32 v208, v194 offset:16388
	ds_read_b32 v184, v194 offset:20480
	ds_read_b32 v183, v194 offset:20484
	ds_read_b32 v177, v194 offset:24576
	ds_read_b32 v176, v194 offset:24580
	ds_read_b32 v160, v194 offset:28672
	ds_read_b32 v159, v194 offset:28676
	ds_read_b32 v153, v194 offset:32768
	ds_read_b32 v152, v194 offset:32772
	ds_read_b32 v146, v194 offset:36864
	ds_read_b32 v145, v194 offset:36868
	ds_read_b32 v140, v194 offset:40960
	ds_read_b32 v139, v194 offset:40964
	ds_read_b32 v133, v194 offset:45056
	ds_read_b32 v132, v194 offset:45060
	ds_read_b32 v124, v194 offset:49152
	ds_read_b32 v123, v194 offset:49156
	ds_read_b32 v116, v194 offset:53248
	ds_read_b32 v115, v194 offset:53252
	ds_read_b32 v108, v194 offset:57344
	ds_read_b32 v107, v194 offset:57348
	ds_read_b32 v101, v194 offset:61440
	ds_read_b32 v100, v194 offset:61444
	ds_read_b32 v237, v195 offset:0
	ds_read_b32 v236, v195 offset:4
	ds_read_b32 v231, v195 offset:4096
	ds_read_b32 v230, v195 offset:4100
	ds_read_b32 v226, v195 offset:8192
	ds_read_b32 v225, v195 offset:8196
	ds_read_b32 v219, v195 offset:12288
	ds_read_b32 v218, v195 offset:12292
	ds_read_b32 v212, v195 offset:16384
	ds_read_b32 v211, v195 offset:16388
	ds_read_b32 v186, v195 offset:20480
	ds_read_b32 v185, v195 offset:20484
	ds_read_b32 v179, v195 offset:24576
	ds_read_b32 v178, v195 offset:24580
	ds_read_b32 v172, v195 offset:28672
	ds_read_b32 v163, v195 offset:28676
	ds_read_b32 v157, v195 offset:32768
	ds_read_b32 v154, v195 offset:32772
	ds_read_b32 v150, v195 offset:36864
	ds_read_b32 v149, v195 offset:36868
	ds_read_b32 v122, v195 offset:40960
	ds_read_b32 v141, v195 offset:40964
	ds_read_b32 v135, v195 offset:45056
	ds_read_b32 v134, v195 offset:45060
	ds_read_b32 v128, v195 offset:49152
	ds_read_b32 v126, v195 offset:49156
	ds_read_b32 v119, v195 offset:53248
	ds_read_b32 v118, v195 offset:53252
	ds_read_b32 v112, v195 offset:57344
	ds_read_b32 v111, v195 offset:57348
	ds_read_b32 v103, v195 offset:61440
	ds_read_b32 v102, v195 offset:61444
	s_waitcnt vmcnt(0) lgkmcnt(0)
	s_mov_b64 s[92:93], -1
	s_and_b64 vcc, exec, s[88:89]
	s_cbranch_vccz .LBB0_463
	v_lshlrev_b32_e32 v86, 16, v81
	v_and_b32_e32 v87, 0xffff0000, v81
	v_lshlrev_b32_e32 v84, 16, v80
	v_and_b32_e32 v85, 0xffff0000, v80
	v_lshlrev_b32_e32 v82, 16, v227
	v_and_b32_e32 v83, 0xffff0000, v227
	s_mov_b64 s[92:93], 0

; __device__ __forceinline__ float bflo(unsigned u) { return __uint_as_float(u << 16); }
; __global__ void __launch_bounds__(NWAVES * 64, 2) mk_fwd(Args args) {
;     ...
;                     for (int tok = 0; tok < 16; ++tok) {
;                         const int m = m0 + tok;
;                         const unsigned ur = pur[tok + 1], uk = puk[tok + 1], uv = puv[tok + 1];
;                         const float cr[2] = {bflo(ur), bfhi(ur)}, ck[2] = {bflo(uk), bfhi(uk)}, cv[2] = {bflo(uv), bfhi(uv)};
;                         float rr[2], kk[2], vv[2], dec[2], aa[2], kkn[2], km[2], bb[2];
;                         rr[0] = cr[0] + (pr[0] - cr[0]) * mu_r.x; rr[1] = cr[1] + (pr[1] - cr[1]) * mu_r.y;
;                         kk[0] = ck[0] + (pk[0] - ck[0]) * mu_k.x; kk[1] = ck[1] + (pk[1] - ck[1]) * mu_k.y;
;                         vv[0] = cv[0] + (pv[0] - cv[0]) * mu_v.x; vv[1] = cv[1] + (pv[1] - cv[1]) * mu_v.y;
;                         dec[0] = __expf(-0.6065306597126334f * sigmoidf_(w0v.x + lw[tok][0])); dec[1] = __expf(-0.6065306597126334f * sigmoidf_(w0v.y + lw[tok][1]));
;                         aa[0] = sigmoidf_(a0v.x + la[tok][0]); aa[1] = sigmoidf_(a0v.y + la[tok][1]);
;                         kkn[0] = kk[0] * kkw.x; kkn[1] = kk[1] * kkw.y;
;                         const float ssq = sum32(kkn[0] * kkn[0] + kkn[1] * kkn[1]);
;                         const float inv = rsqrtf(ssq + 1e-12f);
;                         kkn[0] *= inv; kkn[1] *= inv;
;                         km[0] = kk[0] * (1.f + (aa[0] - 1.f) * kaw.x); km[1] = kk[1] * (1.f + (aa[1] - 1.f) * kaw.y);
;                         bb[0] = kkn[0] * aa[0]; bb[1] = kkn[1] * aa[1];
;                         const float rkd = sum32(rr[0] * km[0] * rkw.x + rr[1] * km[1] * rkw.y);
;                         if (kp == 0) rkdot[(size_t)m * 16 + h] = rkd;
;                         char* rec = scanrec + (rec0 + tok) * REC;
;                         *(f32x2*)(rec + kp * 8) = (f32x2){dec[0], dec[1]};
;                         *(f32x2*)(rec + 256 + kp * 8) = (f32x2){kkn[0], kkn[1]};
;                         *(f32x2*)(rec + 512 + kp * 8) = (f32x2){bb[0], bb[1]};
;                         *(unsigned*)(rec + 768 + kp * 4) = cvtpk(rr[0], rr[1]);
;                         *(unsigned*)(rec + 896 + kp * 4) = cvtpk(km[0], km[1]);
;                         *(unsigned*)(rec + 1024 + kp * 4) = cvtpk(vv[0], vv[1]);
.LBB0_466:
	s_waitcnt lgkmcnt(3)
	s_nop 0
	s_nop 0
	v_lshlrev_b32_e32 v238, 16, v235
	v_and_b32_e32 v235, 0xffff0000, v235
	s_waitcnt vmcnt(2)
	v_sub_f32_e32 v32, v86, v238
	v_sub_f32_e32 v86, v87, v235
	v_add_f32_e32 v87, v44, v237
	v_add_f32_e32 v164, v45, v236
	v_mul_f32_e32 v87, 0xbfb8aa3b, v87
	v_mul_f32_e32 v164, 0xbfb8aa3b, v164
	v_exp_f32_e32 v87, v87
	v_exp_f32_e32 v164, v164
	v_lshlrev_b32_e32 v80, 16, v234
	v_and_b32_e32 v81, 0xffff0000, v234
	s_waitcnt vmcnt(1)
	v_pk_add_f32 v[84:85], v[84:85], v[80:81] neg_lo:[0,1] neg_hi:[0,1]
	v_fma_f32 v237, v53, v86, v235
	v_add_f32_e32 v86, 1.0, v87
	v_add_f32_e32 v87, 1.0, v164
	v_pk_fma_f32 v[164:165], v[50:51], v[84:85], v[80:81]
	v_rcp_f32_e32 v86, v86
	v_pk_mul_f32 v[84:85], v[42:43], v[164:165]
	v_rcp_f32_e32 v87, v87
	v_pk_mul_f32 v[240:241], v[84:85], v[84:85]
	v_fma_f32 v32, v52, v32, v238
	v_add_f32_e32 v194, v240, v241
	s_nop 1
	v_add_f32_dpp v194, v194, v194 quad_perm:[1,0,3,2] row_mask:0xf bank_mask:0xf bound_ctrl:1
	s_nop 1
	v_add_f32_dpp v194, v194, v194 quad_perm:[2,3,0,1] row_mask:0xf bank_mask:0xf bound_ctrl:1
	s_nop 1
	v_add_f32_dpp v194, v194, v194 row_half_mirror row_mask:0xf bank_mask:0xf bound_ctrl:1
	s_nop 1
	v_add_f32_dpp v239, v194, v194 row_mirror row_mask:0xf bank_mask:0xf bound_ctrl:1
	v_add_f32_e32 v194, -1.0, v86
	v_fma_f32 v194, v40, v194, 1.0
	v_mul_f32_e32 v227, v164, v194
	v_add_f32_e32 v164, -1.0, v87
	v_fma_f32 v164, v41, v164, 1.0
	v_mul_f32_e32 v234, v165, v164
	v_mul_f32_e32 v165, v237, v234
	v_mul_f32_e32 v164, v32, v227
	v_mul_f32_e32 v165, v39, v165
	v_fmac_f32_e32 v165, v38, v164
	ds_bpermute_b32 v240, v96, v239
	s_nop 0
	v_add_f32_dpp v164, v165, v165 quad_perm:[1,0,3,2] row_mask:0xf bank_mask:0xf bound_ctrl:1
	s_nop 1
	v_add_f32_dpp v164, v164, v164 quad_perm:[2,3,0,1] row_mask:0xf bank_mask:0xf bound_ctrl:1
	s_nop 1
	v_add_f32_dpp v164, v164, v164 row_half_mirror row_mask:0xf bank_mask:0xf bound_ctrl:1
	s_nop 1
	v_add_f32_dpp v236, v164, v164 row_mirror row_mask:0xf bank_mask:0xf bound_ctrl:1
	ds_bpermute_b32 v241, v96, v236
	s_and_saveexec_b64 s[42:43], s[6:7]
	s_cbranch_execz .LBB0_468
	s_lshl_b64 s[80:81], s[80:81], 6
	v_lshl_add_u64 v[164:165], v[68:69], 0, s[80:81]
	s_waitcnt lgkmcnt(0)
	v_add_f32_e32 v194, v236, v241
	global_store_dword v[164:165], v194, off
.LBB0_468:
	s_or_b64 exec, exec, s[42:43]
	s_nop 0
	v_lshlrev_b32_e32 v236, 16, v224
	s_nop 0
	v_and_b32_e32 v28, 0xffff0000, v224
	v_add_f32_e32 v164, v46, v233
	v_mul_f32_e32 v164, 0xbfb8aa3b, v164
	v_exp_f32_e32 v164, v164
	s_waitcnt vmcnt(0)
	v_sub_f32_e32 v82, v82, v236
	v_fma_f32 v194, v48, v82, v236
	v_sub_f32_e32 v82, v83, v28
	v_add_f32_e32 v83, v47, v232
	v_fma_f32 v195, v49, v82, v28
	v_add_f32_e32 v82, 1.0, v164
	v_mul_f32_e32 v83, 0xbfb8aa3b, v83
	s_waitcnt lgkmcnt(1)
	v_add_f32_e32 v164, v239, v240
	v_exp_f32_e32 v83, v83
	v_add_f32_e32 v164, 0x2b8cbccc, v164
	v_mul_f32_e32 v165, 0x4b800000, v164
	v_cmp_gt_f32_e32 vcc, s33, v164
	v_add_f32_e32 v83, 1.0, v83
	v_rcp_f32_e32 v82, v82
	v_cndmask_b32_e32 v164, v164, v165, vcc
	v_rsq_f32_e32 v164, v164
	v_rcp_f32_e32 v83, v83
	v_mul_f32_e32 v82, 0xbf1b4598, v82
	s_nop 0
	v_mul_f32_e32 v165, 0x45800000, v164
	v_cndmask_b32_e32 v164, v164, v165, vcc
	v_mul_f32_e32 v83, 0xbf1b4598, v83
	v_pk_mul_f32 v[84:85], v[84:85], v[164:165] op_sel_hi:[1,0]
	s_nop 0
	v_or_b32_e32 v33, s97, v78
	v_mov_b64_e32 v[164:165], s[50:51]
	s_movk_i32 s80, 0x480
	v_mul_f32_e32 v82, 0x3fb8aa3b, v82
	v_mul_f32_e32 v83, 0x3fb8aa3b, v83
	v_mad_u64_u32 v[164:165], s[42:43], v33, s80, v[164:165]
	v_exp_f32_e32 v82, v82
	v_exp_f32_e32 v83, v83
	v_mov_b32_e32 v78, v165
	v_mad_u64_u32 v[78:79], s[42:43], v79, s80, v[78:79]
	v_mov_b32_e32 v165, v78
	v_pk_mul_f32 v[86:87], v[86:87], v[84:85]
	v_lshl_add_u64 v[78:79], v[164:165], 0, v[66:67]
	global_store_dwordx2 v[78:79], v[82:83], off
	global_store_dwordx2 v[78:79], v[84:85], off offset:256
	global_store_dwordx2 v[78:79], v[86:87], off offset:512
	v_add_f32_e32 v85, v44, v231
	v_add_f32_e32 v86, v45, v230
	v_mul_f32_e32 v85, 0xbfb8aa3b, v85
	v_mul_f32_e32 v86, 0xbfb8aa3b, v86
	v_exp_f32_e32 v85, v85
	v_exp_f32_e32 v86, v86
	v_cvt_pk_bf16_f32 v82, v32, v237
	v_lshl_add_u64 v[32:33], v[164:165], 0, v[70:71]
	v_lshlrev_b32_e32 v224, 16, v221
	global_store_dword v[32:33], v82, off offset:768
	v_and_b32_e32 v221, 0xffff0000, v221
	v_lshlrev_b32_e32 v82, 16, v220
	v_and_b32_e32 v83, 0xffff0000, v220
	v_sub_f32_e32 v84, v238, v224
	v_fma_f32 v220, v52, v84, v224
	v_sub_f32_e32 v84, v235, v221
	v_pk_add_f32 v[80:81], v[80:81], v[82:83] neg_lo:[0,1] neg_hi:[0,1]
	v_fma_f32 v230, v53, v84, v221
	v_add_f32_e32 v84, 1.0, v85
	v_add_f32_e32 v85, 1.0, v86
	v_pk_fma_f32 v[86:87], v[50:51], v[80:81], v[82:83]
	v_rcp_f32_e32 v84, v84
	v_pk_mul_f32 v[80:81], v[42:43], v[86:87]
	v_rcp_f32_e32 v85, v85
	v_pk_mul_f32 v[164:165], v[80:81], v[80:81]
	s_nop 0
	v_add_f32_e32 v164, v164, v165
	s_nop 1
	v_add_f32_dpp v164, v164, v164 quad_perm:[1,0,3,2] row_mask:0xf bank_mask:0xf bound_ctrl:1
	s_nop 1
	v_add_f32_dpp v164, v164, v164 quad_perm:[2,3,0,1] row_mask:0xf bank_mask:0xf bound_ctrl:1
	s_nop 1
	v_add_f32_dpp v164, v164, v164 row_half_mirror row_mask:0xf bank_mask:0xf bound_ctrl:1
	s_nop 1
	v_add_f32_dpp v231, v164, v164 row_mirror row_mask:0xf bank_mask:0xf bound_ctrl:1
	v_add_f32_e32 v164, -1.0, v84
	v_fma_f32 v164, v40, v164, 1.0
	v_mul_f32_e32 v86, v86, v164
	v_add_f32_e32 v164, -1.0, v85
	v_fma_f32 v164, v41, v164, 1.0
	v_mul_f32_e32 v87, v87, v164
	v_mul_f32_e32 v165, v230, v87
	v_mul_f32_e32 v164, v220, v86
	v_mul_f32_e32 v165, v39, v165
	v_fmac_f32_e32 v165, v38, v164
	ds_bpermute_b32 v232, v96, v231
	s_nop 0
	v_add_f32_dpp v164, v165, v165 quad_perm:[1,0,3,2] row_mask:0xf bank_mask:0xf bound_ctrl:1
	s_nop 1
	v_add_f32_dpp v164, v164, v164 quad_perm:[2,3,0,1] row_mask:0xf bank_mask:0xf bound_ctrl:1
	s_nop 1
	v_add_f32_dpp v164, v164, v164 row_half_mirror row_mask:0xf bank_mask:0xf bound_ctrl:1
	s_nop 1
	v_add_f32_dpp v233, v164, v164 row_mirror row_mask:0xf bank_mask:0xf bound_ctrl:1
	ds_bpermute_b32 v235, v96, v233
	v_cvt_pk_bf16_f32 v164, v227, v234
	global_store_dword v[32:33], v164, off offset:896
	v_cvt_pk_bf16_f32 v164, v194, v195
	global_store_dword v[32:33], v164, off offset:1024
	s_and_saveexec_b64 s[42:43], s[6:7]
	s_cbranch_execz .LBB0_470
	s_lshl_b64 s[80:81], s[90:91], 6
	v_lshl_add_u64 v[164:165], v[68:69], 0, s[80:81]
	s_waitcnt lgkmcnt(0)
	v_add_f32_e32 v194, v233, v235
	global_store_dword v[164:165], v194, off
; __device__ __forceinline__ float bflo(unsigned u) { return __uint_as_float(u << 16); }
; __global__ void __launch_bounds__(NWAVES * 64, 2) mk_fwd(Args args) {
;     ...
;                     for (int tok = 0; tok < 16; ++tok) {
;                         const int m = m0 + tok;
;                         const unsigned ur = pur[tok + 1], uk = puk[tok + 1], uv = puv[tok + 1];
;                         const float cr[2] = {bflo(ur), bfhi(ur)}, ck[2] = {bflo(uk), bfhi(uk)}, cv[2] = {bflo(uv), bfhi(uv)};
;                         float rr[2], kk[2], vv[2], dec[2], aa[2], kkn[2], km[2], bb[2];
;                         rr[0] = cr[0] + (pr[0] - cr[0]) * mu_r.x; rr[1] = cr[1] + (pr[1] - cr[1]) * mu_r.y;
;                         kk[0] = ck[0] + (pk[0] - ck[0]) * mu_k.x; kk[1] = ck[1] + (pk[1] - ck[1]) * mu_k.y;
;                         vv[0] = cv[0] + (pv[0] - cv[0]) * mu_v.x; vv[1] = cv[1] + (pv[1] - cv[1]) * mu_v.y;
;                         dec[0] = __expf(-0.6065306597126334f * sigmoidf_(w0v.x + lw[tok][0])); dec[1] = __expf(-0.6065306597126334f * sigmoidf_(w0v.y + lw[tok][1]));
;                         aa[0] = sigmoidf_(a0v.x + la[tok][0]); aa[1] = sigmoidf_(a0v.y + la[tok][1]);
;                         kkn[0] = kk[0] * kkw.x; kkn[1] = kk[1] * kkw.y;
;                         const float ssq = sum32(kkn[0] * kkn[0] + kkn[1] * kkn[1]);
;                         const float inv = rsqrtf(ssq + 1e-12f);
;                         kkn[0] *= inv; kkn[1] *= inv;
;                         km[0] = kk[0] * (1.f + (aa[0] - 1.f) * kaw.x); km[1] = kk[1] * (1.f + (aa[1] - 1.f) * kaw.y);
;                         bb[0] = kkn[0] * aa[0]; bb[1] = kkn[1] * aa[1];
;                         const float rkd = sum32(rr[0] * km[0] * rkw.x + rr[1] * km[1] * rkw.y);
;                         if (kp == 0) rkdot[(size_t)m * 16 + h] = rkd;
;                         char* rec = scanrec + (rec0 + tok) * REC;
;                         *(f32x2*)(rec + kp * 8) = (f32x2){dec[0], dec[1]};
;                         *(f32x2*)(rec + 256 + kp * 8) = (f32x2){kkn[0], kkn[1]};
;                         *(f32x2*)(rec + 512 + kp * 8) = (f32x2){bb[0], bb[1]};
;                         *(unsigned*)(rec + 768 + kp * 4) = cvtpk(rr[0], rr[1]);
;                         *(unsigned*)(rec + 896 + kp * 4) = cvtpk(km[0], km[1]);
;                         *(unsigned*)(rec + 1024 + kp * 4) = cvtpk(vv[0], vv[1]);
.LBB0_470:
	s_or_b64 exec, exec, s[42:43]
	v_lshlrev_b32_e32 v227, 16, v216
	s_nop 0
	s_nop 0
	v_sub_f32_e32 v29, v236, v227
	v_fma_f32 v194, v48, v29, v227
	v_add_f32_e32 v164, v46, v229
	v_add_f32_e32 v29, v47, v228
	v_mul_f32_e32 v164, 0xbfb8aa3b, v164
	v_mul_f32_e32 v29, 0xbfb8aa3b, v29
	v_exp_f32_e32 v164, v164
	v_exp_f32_e32 v29, v29
	v_and_b32_e32 v216, 0xffff0000, v216
	v_sub_f32_e32 v28, v28, v216
	v_fma_f32 v195, v49, v28, v216
	v_add_f32_e32 v28, 1.0, v164
	v_add_f32_e32 v29, 1.0, v29
	s_waitcnt lgkmcnt(1)
	v_add_f32_e32 v164, v231, v232
	v_rcp_f32_e32 v28, v28
	v_rcp_f32_e32 v29, v29
	v_add_f32_e32 v164, 0x2b8cbccc, v164
	v_mul_f32_e32 v165, 0x4b800000, v164
	v_cmp_gt_f32_e32 vcc, s33, v164
	v_mul_f32_e32 v28, 0xbf1b4598, v28
	v_mul_f32_e32 v29, 0xbf1b4598, v29
	v_cndmask_b32_e32 v164, v164, v165, vcc
	v_rsq_f32_e32 v164, v164
	v_mul_f32_e32 v28, 0x3fb8aa3b, v28
	v_mul_f32_e32 v29, 0x3fb8aa3b, v29
	v_exp_f32_e32 v28, v28
	v_exp_f32_e32 v29, v29
	v_mul_f32_e32 v165, 0x45800000, v164
	v_cndmask_b32_e32 v164, v164, v165, vcc
	v_pk_mul_f32 v[80:81], v[80:81], v[164:165] op_sel_hi:[1,0]
	s_nop 0
	v_pk_mul_f32 v[84:85], v[84:85], v[80:81]
	s_nop 0
	global_store_dwordx2 v[78:79], v[28:29], off offset:1152
	global_store_dwordx2 v[78:79], v[80:81], off offset:1408
	global_store_dwordx2 v[78:79], v[84:85], off offset:1664
	v_add_f32_e32 v81, v44, v226
	v_cvt_pk_bf16_f32 v28, v220, v230
	v_mul_f32_e32 v81, 0xbfb8aa3b, v81
	v_add_f32_e32 v85, v45, v225
	global_store_dword v[32:33], v28, off offset:1920
	v_lshlrev_b32_e32 v28, 16, v213
	v_and_b32_e32 v29, 0xffff0000, v213
	v_exp_f32_e32 v81, v81
	v_mul_f32_e32 v85, 0xbfb8aa3b, v85
	v_exp_f32_e32 v85, v85
	v_pk_add_f32 v[82:83], v[82:83], v[28:29] neg_lo:[0,1] neg_hi:[0,1]
	v_and_b32_e32 v84, 0xffff0000, v214
	v_pk_fma_f32 v[164:165], v[50:51], v[82:83], v[28:29]
	v_lshlrev_b32_e32 v220, 16, v214
	v_sub_f32_e32 v80, v221, v84
	v_pk_mul_f32 v[82:83], v[42:43], v[164:165]
	v_sub_f32_e32 v34, v224, v220
	v_fma_f32 v214, v53, v80, v84
	v_add_f32_e32 v80, 1.0, v81
	v_pk_mul_f32 v[224:225], v[82:83], v[82:83]
	v_rcp_f32_e32 v80, v80
	v_add_f32_e32 v81, 1.0, v85
	v_add_f32_e32 v85, v224, v225
	v_rcp_f32_e32 v81, v81
	v_fma_f32 v34, v52, v34, v220
	v_add_f32_dpp v85, v85, v85 quad_perm:[1,0,3,2] row_mask:0xf bank_mask:0xf bound_ctrl:1
	v_cvt_pk_bf16_f32 v86, v86, v87
	global_store_dword v[32:33], v86, off offset:2048
	v_cvt_pk_bf16_f32 v86, v194, v195
	global_store_dword v[32:33], v86, off offset:2176
	v_add_f32_dpp v85, v85, v85 quad_perm:[2,3,0,1] row_mask:0xf bank_mask:0xf bound_ctrl:1
	s_nop 1
	v_add_f32_dpp v85, v85, v85 row_half_mirror row_mask:0xf bank_mask:0xf bound_ctrl:1
	s_nop 1
	v_add_f32_dpp v221, v85, v85 row_mirror row_mask:0xf bank_mask:0xf bound_ctrl:1
	v_add_f32_e32 v85, -1.0, v80
	v_fma_f32 v85, v40, v85, 1.0
	v_mul_f32_e32 v85, v164, v85
	v_add_f32_e32 v164, -1.0, v81
	v_fma_f32 v164, v41, v164, 1.0
	v_mul_f32_e32 v213, v165, v164
	v_mul_f32_e32 v165, v214, v213
	v_mul_f32_e32 v164, v34, v85
	v_mul_f32_e32 v165, v39, v165
	v_fmac_f32_e32 v165, v38, v164
	ds_bpermute_b32 v224, v96, v221
	s_nop 0
	v_add_f32_dpp v164, v165, v165 quad_perm:[1,0,3,2] row_mask:0xf bank_mask:0xf bound_ctrl:1
	s_nop 1
	v_add_f32_dpp v164, v164, v164 quad_perm:[2,3,0,1] row_mask:0xf bank_mask:0xf bound_ctrl:1
	s_nop 1
	v_add_f32_dpp v164, v164, v164 row_half_mirror row_mask:0xf bank_mask:0xf bound_ctrl:1
	s_nop 1
	v_add_f32_dpp v225, v164, v164 row_mirror row_mask:0xf bank_mask:0xf bound_ctrl:1
	ds_bpermute_b32 v226, v96, v225
	s_and_saveexec_b64 s[42:43], s[6:7]
	s_cbranch_execz .LBB0_472
	s_lshl_b64 s[80:81], s[86:87], 6
	v_lshl_add_u64 v[86:87], v[68:69], 0, s[80:81]
	s_waitcnt lgkmcnt(0)
	v_add_f32_e32 v164, v225, v226
	global_store_dword v[86:87], v164, off
.LBB0_472:
	s_or_b64 exec, exec, s[42:43]
	s_nop 0
	v_lshlrev_b32_e32 v87, 16, v210
	s_nop 0
	v_and_b32_e32 v30, 0xffff0000, v210
	v_add_f32_e32 v164, v46, v223
	v_mul_f32_e32 v164, 0xbfb8aa3b, v164
	v_exp_f32_e32 v164, v164
	v_sub_f32_e32 v86, v227, v87
	v_fma_f32 v194, v48, v86, v87
	v_sub_f32_e32 v86, v216, v30
	v_fma_f32 v195, v49, v86, v30
	v_add_f32_e32 v86, 1.0, v164
	v_rcp_f32_e32 v86, v86
	v_add_f32_e32 v164, v47, v222
	v_mul_f32_e32 v164, 0xbfb8aa3b, v164
	v_exp_f32_e32 v165, v164
	v_mul_f32_e32 v86, 0xbf1b4598, v86
	v_mul_f32_e32 v86, 0x3fb8aa3b, v86
	v_exp_f32_e32 v164, v86
	v_add_f32_e32 v86, 1.0, v165
	s_waitcnt lgkmcnt(1)
; __device__ __forceinline__ float bflo(unsigned u) { return __uint_as_float(u << 16); }
; __global__ void __launch_bounds__(NWAVES * 64, 2) mk_fwd(Args args) {
;     ...
;                     for (int tok = 0; tok < 16; ++tok) {
;                         const int m = m0 + tok;
;                         const unsigned ur = pur[tok + 1], uk = puk[tok + 1], uv = puv[tok + 1];
;                         const float cr[2] = {bflo(ur), bfhi(ur)}, ck[2] = {bflo(uk), bfhi(uk)}, cv[2] = {bflo(uv), bfhi(uv)};
;                         float rr[2], kk[2], vv[2], dec[2], aa[2], kkn[2], km[2], bb[2];
;                         rr[0] = cr[0] + (pr[0] - cr[0]) * mu_r.x; rr[1] = cr[1] + (pr[1] - cr[1]) * mu_r.y;
;                         kk[0] = ck[0] + (pk[0] - ck[0]) * mu_k.x; kk[1] = ck[1] + (pk[1] - ck[1]) * mu_k.y;
;                         vv[0] = cv[0] + (pv[0] - cv[0]) * mu_v.x; vv[1] = cv[1] + (pv[1] - cv[1]) * mu_v.y;
;                         dec[0] = __expf(-0.6065306597126334f * sigmoidf_(w0v.x + lw[tok][0])); dec[1] = __expf(-0.6065306597126334f * sigmoidf_(w0v.y + lw[tok][1]));
;                         aa[0] = sigmoidf_(a0v.x + la[tok][0]); aa[1] = sigmoidf_(a0v.y + la[tok][1]);
;                         kkn[0] = kk[0] * kkw.x; kkn[1] = kk[1] * kkw.y;
;                         const float ssq = sum32(kkn[0] * kkn[0] + kkn[1] * kkn[1]);
;                         const float inv = rsqrtf(ssq + 1e-12f);
;                         kkn[0] *= inv; kkn[1] *= inv;
;                         km[0] = kk[0] * (1.f + (aa[0] - 1.f) * kaw.x); km[1] = kk[1] * (1.f + (aa[1] - 1.f) * kaw.y);
;                         bb[0] = kkn[0] * aa[0]; bb[1] = kkn[1] * aa[1];
;                         const float rkd = sum32(rr[0] * km[0] * rkw.x + rr[1] * km[1] * rkw.y);
;                         if (kp == 0) rkdot[(size_t)m * 16 + h] = rkd;
;                         char* rec = scanrec + (rec0 + tok) * REC;
;                         *(f32x2*)(rec + kp * 8) = (f32x2){dec[0], dec[1]};
;                         *(f32x2*)(rec + 256 + kp * 8) = (f32x2){kkn[0], kkn[1]};
;                         *(f32x2*)(rec + 512 + kp * 8) = (f32x2){bb[0], bb[1]};
;                         *(unsigned*)(rec + 768 + kp * 4) = cvtpk(rr[0], rr[1]);
;                         *(unsigned*)(rec + 896 + kp * 4) = cvtpk(km[0], km[1]);
;                         *(unsigned*)(rec + 1024 + kp * 4) = cvtpk(vv[0], vv[1]);
	v_add_f32_e32 v165, v221, v224
	v_add_f32_e32 v165, 0x2b8cbccc, v165
	v_rcp_f32_e32 v86, v86
	v_mul_f32_e32 v210, 0x4b800000, v165
	v_cmp_gt_f32_e32 vcc, s33, v165
	s_nop 0
	v_mul_f32_e32 v86, 0xbf1b4598, v86
	v_cndmask_b32_e32 v165, v165, v210, vcc
	v_rsq_f32_e32 v210, v165
	v_mul_f32_e32 v86, 0x3fb8aa3b, v86
	v_exp_f32_e32 v165, v86
	s_nop 0
	v_mul_f32_e32 v86, 0x45800000, v210
	v_cndmask_b32_e32 v86, v210, v86, vcc
	v_pk_mul_f32 v[82:83], v[82:83], v[86:87] op_sel_hi:[1,0]
	v_lshlrev_b32_e32 v210, 16, v206
	v_pk_mul_f32 v[80:81], v[80:81], v[82:83]
	global_store_dwordx2 v[78:79], v[164:165], off offset:2304
	global_store_dwordx2 v[78:79], v[82:83], off offset:2560
	global_store_dwordx2 v[78:79], v[80:81], off offset:2816
	v_add_f32_e32 v81, v44, v219
	v_add_f32_e32 v82, v45, v218
	v_mul_f32_e32 v81, 0xbfb8aa3b, v81
	v_mul_f32_e32 v82, 0xbfb8aa3b, v82
	v_cvt_pk_bf16_f32 v34, v34, v214
	v_exp_f32_e32 v81, v81
	v_exp_f32_e32 v82, v82
	global_store_dword v[32:33], v34, off offset:3072
	v_lshlrev_b32_e32 v34, 16, v207
	v_and_b32_e32 v35, 0xffff0000, v207
	v_and_b32_e32 v83, 0xffff0000, v206
	v_sub_f32_e32 v80, v220, v210
	v_pk_add_f32 v[28:29], v[28:29], v[34:35] neg_lo:[0,1] neg_hi:[0,1]
	v_fma_f32 v207, v52, v80, v210
	v_sub_f32_e32 v80, v84, v83
	v_pk_fma_f32 v[164:165], v[50:51], v[28:29], v[34:35]
	v_fma_f32 v214, v53, v80, v83
	v_add_f32_e32 v80, 1.0, v81
	v_add_f32_e32 v81, 1.0, v82
	v_pk_mul_f32 v[28:29], v[42:43], v[164:165]
	v_rcp_f32_e32 v81, v81
	v_pk_mul_f32 v[218:219], v[28:29], v[28:29]
	v_rcp_f32_e32 v80, v80
	v_add_f32_e32 v82, v218, v219
	v_add_f32_e32 v84, -1.0, v81
	v_fma_f32 v84, v41, v84, 1.0
	v_add_f32_dpp v82, v82, v82 quad_perm:[1,0,3,2] row_mask:0xf bank_mask:0xf bound_ctrl:1
	v_mul_f32_e32 v84, v165, v84
	v_cvt_pk_bf16_f32 v85, v85, v213
	global_store_dword v[32:33], v85, off offset:3200
	v_add_f32_dpp v82, v82, v82 quad_perm:[2,3,0,1] row_mask:0xf bank_mask:0xf bound_ctrl:1
	v_cvt_pk_bf16_f32 v85, v194, v195
	global_store_dword v[32:33], v85, off offset:3328
	s_nop 0
	v_add_f32_dpp v82, v82, v82 row_half_mirror row_mask:0xf bank_mask:0xf bound_ctrl:1
	s_nop 1
	v_add_f32_dpp v216, v82, v82 row_mirror row_mask:0xf bank_mask:0xf bound_ctrl:1
	v_add_f32_e32 v82, -1.0, v80
	v_fma_f32 v82, v40, v82, 1.0
	v_mul_f32_e32 v82, v164, v82
	v_mul_f32_e32 v164, v214, v84
	v_mul_f32_e32 v86, v207, v82
	v_mul_f32_e32 v164, v39, v164
	v_fmac_f32_e32 v164, v38, v86
	ds_bpermute_b32 v218, v96, v216
	s_nop 0
	v_add_f32_dpp v86, v164, v164 quad_perm:[1,0,3,2] row_mask:0xf bank_mask:0xf bound_ctrl:1
	s_nop 1
	v_add_f32_dpp v86, v86, v86 quad_perm:[2,3,0,1] row_mask:0xf bank_mask:0xf bound_ctrl:1
	s_nop 1
	v_add_f32_dpp v86, v86, v86 row_half_mirror row_mask:0xf bank_mask:0xf bound_ctrl:1
	s_nop 1
	v_add_f32_dpp v86, v86, v86 row_mirror row_mask:0xf bank_mask:0xf bound_ctrl:1
	ds_bpermute_b32 v206, v96, v86
	s_and_saveexec_b64 s[42:43], s[6:7]
	s_cbranch_execz .LBB0_474
	s_lshl_b64 s[80:81], s[82:83], 6
	v_lshl_add_u64 v[164:165], v[68:69], 0, s[80:81]
	s_waitcnt lgkmcnt(0)
	v_add_f32_e32 v85, v86, v206
	global_store_dword v[164:165], v85, off
.LBB0_474:
	s_or_b64 exec, exec, s[42:43]
	s_nop 0
	s_waitcnt lgkmcnt(0)
	v_lshlrev_b32_e32 v206, 16, v187
	s_nop 0
	v_sub_f32_e32 v31, v87, v206
	v_add_f32_e32 v85, v46, v217
	v_mul_f32_e32 v85, 0xbfb8aa3b, v85
	v_fma_f32 v194, v48, v31, v206
	v_add_f32_e32 v31, v47, v215
	v_exp_f32_e32 v85, v85
	v_mul_f32_e32 v31, 0xbfb8aa3b, v31
	v_exp_f32_e32 v31, v31
	v_and_b32_e32 v86, 0xffff0000, v187
	v_sub_f32_e32 v30, v30, v86
	v_fma_f32 v195, v49, v30, v86
	v_add_f32_e32 v30, 1.0, v85
	v_add_f32_e32 v85, v216, v218
	v_add_f32_e32 v31, 1.0, v31
	v_add_f32_e32 v85, 0x2b8cbccc, v85
	v_rcp_f32_e32 v30, v30
	v_rcp_f32_e32 v31, v31
	v_mul_f32_e32 v87, 0x4b800000, v85
	v_cmp_gt_f32_e32 vcc, s33, v85
	v_mul_f32_e32 v30, 0xbf1b4598, v30
	v_mul_f32_e32 v31, 0xbf1b4598, v31
	v_cndmask_b32_e32 v85, v85, v87, vcc
	v_rsq_f32_e32 v85, v85
	v_mul_f32_e32 v30, 0x3fb8aa3b, v30
	v_mul_f32_e32 v31, 0x3fb8aa3b, v31
	v_exp_f32_e32 v30, v30
	v_exp_f32_e32 v31, v31
	v_mul_f32_e32 v87, 0x45800000, v85
	v_cndmask_b32_e32 v164, v85, v87, vcc
	v_pk_mul_f32 v[28:29], v[28:29], v[164:165] op_sel_hi:[1,0]
	s_nop 0
	v_pk_mul_f32 v[80:81], v[80:81], v[28:29]
	s_nop 0
	global_store_dwordx2 v[78:79], v[30:31], off offset:3456
	global_store_dwordx2 v[78:79], v[28:29], off offset:3712
	global_store_dwordx2 v[78:79], v[80:81], off offset:3968
	v_add_f32_e32 v80, v44, v212
	s_movk_i32 s42, 0x1000
	v_mul_f32_e32 v80, 0xbfb8aa3b, v80
	v_add_f32_e32 v81, v45, v211
	v_add_co_u32_e32 v28, vcc, s42, v32
	v_exp_f32_e32 v80, v80
	v_mul_f32_e32 v81, 0xbfb8aa3b, v81
	v_cvt_pk_bf16_f32 v24, v207, v214
	v_addc_co_u32_e32 v29, vcc, 0, v33, vcc
	v_lshlrev_b32_e32 v187, 16, v182
	v_exp_f32_e32 v81, v81
	global_store_dword v[28:29], v24, off offset:128
	v_and_b32_e32 v87, 0xffff0000, v182
	v_sub_f32_e32 v24, v210, v187
	v_fma_f32 v182, v52, v24, v187
	v_sub_f32_e32 v24, v83, v87
	v_fma_f32 v207, v53, v24, v87
	v_add_f32_e32 v24, 1.0, v80
	v_rcp_f32_e32 v80, v24
	v_add_f32_e32 v24, 1.0, v81
	v_rcp_f32_e32 v81, v24
	v_lshlrev_b32_e32 v30, 16, v181
	v_and_b32_e32 v31, 0xffff0000, v181
	v_pk_add_f32 v[34:35], v[34:35], v[30:31] neg_lo:[0,1] neg_hi:[0,1]
	v_add_f32_e32 v85, -1.0, v81
	v_pk_fma_f32 v[164:165], v[50:51], v[34:35], v[30:31]
	v_add_f32_e32 v83, -1.0, v80
	v_fma_f32 v85, v41, v85, 1.0
	v_fma_f32 v83, v40, v83, 1.0
	v_mul_f32_e32 v85, v165, v85
	v_pk_mul_f32 v[34:35], v[42:43], v[164:165]
	v_mul_f32_e32 v83, v164, v83
	v_mul_f32_e32 v165, v207, v85
	v_pk_mul_f32 v[210:211], v[34:35], v[34:35]
	v_mul_f32_e32 v164, v182, v83
	v_mul_f32_e32 v165, v39, v165
	v_add_f32_e32 v24, v210, v211
	v_fmac_f32_e32 v165, v38, v164
	v_cvt_pk_bf16_f32 v82, v82, v84
	global_store_dword v[28:29], v82, off offset:256
	v_add_f32_dpp v24, v24, v24 quad_perm:[1,0,3,2] row_mask:0xf bank_mask:0xf bound_ctrl:1
	v_add_f32_dpp v164, v165, v165 quad_perm:[1,0,3,2] row_mask:0xf bank_mask:0xf bound_ctrl:1
	v_cvt_pk_bf16_f32 v82, v194, v195
	global_store_dword v[28:29], v82, off offset:384
	v_add_f32_dpp v24, v24, v24 quad_perm:[2,3,0,1] row_mask:0xf bank_mask:0xf bound_ctrl:1
	v_add_f32_dpp v164, v164, v164 quad_perm:[2,3,0,1] row_mask:0xf bank_mask:0xf bound_ctrl:1
	s_nop 0
	v_add_f32_dpp v24, v24, v24 row_half_mirror row_mask:0xf bank_mask:0xf bound_ctrl:1
	v_add_f32_dpp v164, v164, v164 row_half_mirror row_mask:0xf bank_mask:0xf bound_ctrl:1
	s_nop 0
	v_add_f32_dpp v24, v24, v24 row_mirror row_mask:0xf bank_mask:0xf bound_ctrl:1
	v_add_f32_dpp v181, v164, v164 row_mirror row_mask:0xf bank_mask:0xf bound_ctrl:1
	ds_bpermute_b32 v210, v96, v24
	ds_bpermute_b32 v211, v96, v181
	s_and_saveexec_b64 s[42:43], s[6:7]
	s_cbranch_execz .LBB0_476
	s_lshl_b64 s[78:79], s[78:79], 6
	v_lshl_add_u64 v[164:165], v[68:69], 0, s[78:79]
	s_waitcnt lgkmcnt(0)
	v_add_f32_e32 v82, v181, v211
	global_store_dword v[164:165], v82, off
; __device__ __forceinline__ float bflo(unsigned u) { return __uint_as_float(u << 16); }
; __global__ void __launch_bounds__(NWAVES * 64, 2) mk_fwd(Args args) {
;     ...
;                     for (int tok = 0; tok < 16; ++tok) {
;                         const int m = m0 + tok;
;                         const unsigned ur = pur[tok + 1], uk = puk[tok + 1], uv = puv[tok + 1];
;                         const float cr[2] = {bflo(ur), bfhi(ur)}, ck[2] = {bflo(uk), bfhi(uk)}, cv[2] = {bflo(uv), bfhi(uv)};
;                         float rr[2], kk[2], vv[2], dec[2], aa[2], kkn[2], km[2], bb[2];
;                         rr[0] = cr[0] + (pr[0] - cr[0]) * mu_r.x; rr[1] = cr[1] + (pr[1] - cr[1]) * mu_r.y;
;                         kk[0] = ck[0] + (pk[0] - ck[0]) * mu_k.x; kk[1] = ck[1] + (pk[1] - ck[1]) * mu_k.y;
;                         vv[0] = cv[0] + (pv[0] - cv[0]) * mu_v.x; vv[1] = cv[1] + (pv[1] - cv[1]) * mu_v.y;
;                         dec[0] = __expf(-0.6065306597126334f * sigmoidf_(w0v.x + lw[tok][0])); dec[1] = __expf(-0.6065306597126334f * sigmoidf_(w0v.y + lw[tok][1]));
;                         aa[0] = sigmoidf_(a0v.x + la[tok][0]); aa[1] = sigmoidf_(a0v.y + la[tok][1]);
;                         kkn[0] = kk[0] * kkw.x; kkn[1] = kk[1] * kkw.y;
;                         const float ssq = sum32(kkn[0] * kkn[0] + kkn[1] * kkn[1]);
;                         const float inv = rsqrtf(ssq + 1e-12f);
;                         kkn[0] *= inv; kkn[1] *= inv;
;                         km[0] = kk[0] * (1.f + (aa[0] - 1.f) * kaw.x); km[1] = kk[1] * (1.f + (aa[1] - 1.f) * kaw.y);
;                         bb[0] = kkn[0] * aa[0]; bb[1] = kkn[1] * aa[1];
;                         const float rkd = sum32(rr[0] * km[0] * rkw.x + rr[1] * km[1] * rkw.y);
;                         if (kp == 0) rkdot[(size_t)m * 16 + h] = rkd;
;                         char* rec = scanrec + (rec0 + tok) * REC;
;                         *(f32x2*)(rec + kp * 8) = (f32x2){dec[0], dec[1]};
;                         *(f32x2*)(rec + 256 + kp * 8) = (f32x2){kkn[0], kkn[1]};
;                         *(f32x2*)(rec + 512 + kp * 8) = (f32x2){bb[0], bb[1]};
;                         *(unsigned*)(rec + 768 + kp * 4) = cvtpk(rr[0], rr[1]);
;                         *(unsigned*)(rec + 896 + kp * 4) = cvtpk(km[0], km[1]);
;                         *(unsigned*)(rec + 1024 + kp * 4) = cvtpk(vv[0], vv[1]);
.LBB0_476:
	s_or_b64 exec, exec, s[42:43]
	s_nop 0
	v_lshlrev_b32_e32 v181, 16, v180
	s_nop 0
	v_and_b32_e32 v20, 0xffff0000, v180
	v_add_f32_e32 v84, v46, v209
	v_mul_f32_e32 v84, 0xbfb8aa3b, v84
	v_exp_f32_e32 v84, v84
	v_sub_f32_e32 v82, v206, v181
	v_fma_f32 v194, v48, v82, v181
	v_sub_f32_e32 v82, v86, v20
	v_fma_f32 v195, v49, v82, v20
	v_add_f32_e32 v82, 1.0, v84
	v_rcp_f32_e32 v82, v82
	v_add_f32_e32 v84, v47, v208
	v_mul_f32_e32 v84, 0xbfb8aa3b, v84
	v_exp_f32_e32 v84, v84
	v_mul_f32_e32 v82, 0xbf1b4598, v82
	v_mul_f32_e32 v82, 0x3fb8aa3b, v82
	s_waitcnt lgkmcnt(1)
	v_add_f32_e32 v24, v24, v210
	v_exp_f32_e32 v164, v82
	v_add_f32_e32 v82, 1.0, v84
	v_add_f32_e32 v24, 0x2b8cbccc, v24
	v_rcp_f32_e32 v82, v82
	v_mul_f32_e32 v84, 0x4b800000, v24
	v_cmp_gt_f32_e32 vcc, s33, v24
	s_movk_i32 s42, 0x1000
	v_mul_f32_e32 v82, 0xbf1b4598, v82
	v_cndmask_b32_e32 v24, v24, v84, vcc
	v_rsq_f32_e32 v24, v24
	v_mul_f32_e32 v82, 0x3fb8aa3b, v82
	v_exp_f32_e32 v165, v82
	s_nop 0
	v_mul_f32_e32 v82, 0x45800000, v24
	v_cndmask_b32_e32 v24, v24, v82, vcc
	v_pk_mul_f32 v[34:35], v[34:35], v[24:25] op_sel_hi:[1,0]
	v_add_co_u32_e32 v24, vcc, s42, v78
	v_pk_mul_f32 v[80:81], v[80:81], v[34:35]
	s_nop 0
	v_addc_co_u32_e32 v25, vcc, 0, v79, vcc
	global_store_dwordx2 v[24:25], v[164:165], off offset:512
	global_store_dwordx2 v[24:25], v[34:35], off offset:768
	global_store_dwordx2 v[24:25], v[80:81], off offset:1024
	v_add_f32_e32 v81, v44, v186
	v_add_f32_e32 v82, v45, v185
	v_mul_f32_e32 v81, 0xbfb8aa3b, v81
	v_mul_f32_e32 v82, 0xbfb8aa3b, v82
	v_cvt_pk_bf16_f32 v34, v182, v207
	v_exp_f32_e32 v81, v81
	v_exp_f32_e32 v82, v82
	global_store_dword v[28:29], v34, off offset:1280
	v_lshlrev_b32_e32 v180, 16, v175
	v_lshlrev_b32_e32 v34, 16, v174
	v_and_b32_e32 v35, 0xffff0000, v174
	v_and_b32_e32 v86, 0xffff0000, v175
	v_sub_f32_e32 v80, v187, v180
	v_pk_add_f32 v[30:31], v[30:31], v[34:35] neg_lo:[0,1] neg_hi:[0,1]
	v_fma_f32 v175, v52, v80, v180
	v_sub_f32_e32 v80, v87, v86
	v_pk_fma_f32 v[164:165], v[50:51], v[30:31], v[34:35]
	v_fma_f32 v87, v53, v80, v86
	v_add_f32_e32 v80, 1.0, v81
	v_add_f32_e32 v81, 1.0, v82
	v_pk_mul_f32 v[30:31], v[42:43], v[164:165]
	v_rcp_f32_e32 v81, v81
	v_pk_mul_f32 v[186:187], v[30:31], v[30:31]
	v_rcp_f32_e32 v80, v80
	v_add_f32_e32 v82, v186, v187
	v_add_f32_e32 v84, -1.0, v81
	v_fma_f32 v84, v41, v84, 1.0
	v_add_f32_dpp v82, v82, v82 quad_perm:[1,0,3,2] row_mask:0xf bank_mask:0xf bound_ctrl:1
	v_mul_f32_e32 v84, v165, v84
	v_mul_f32_e32 v165, v87, v84
	v_add_f32_dpp v82, v82, v82 quad_perm:[2,3,0,1] row_mask:0xf bank_mask:0xf bound_ctrl:1
	v_mul_f32_e32 v165, v39, v165
	v_cvt_pk_bf16_f32 v83, v83, v85
	global_store_dword v[28:29], v83, off offset:1408
	v_add_f32_dpp v82, v82, v82 row_half_mirror row_mask:0xf bank_mask:0xf bound_ctrl:1
	v_cvt_pk_bf16_f32 v83, v194, v195
	global_store_dword v[28:29], v83, off offset:1536
	s_nop 0
	v_add_f32_dpp v182, v82, v82 row_mirror row_mask:0xf bank_mask:0xf bound_ctrl:1
	v_add_f32_e32 v82, -1.0, v80
	v_fma_f32 v82, v40, v82, 1.0
	v_mul_f32_e32 v82, v164, v82
	v_mul_f32_e32 v164, v175, v82
	v_fmac_f32_e32 v165, v38, v164
	ds_bpermute_b32 v185, v96, v182
	s_nop 0
	v_add_f32_dpp v164, v165, v165 quad_perm:[1,0,3,2] row_mask:0xf bank_mask:0xf bound_ctrl:1
	s_nop 1
	v_add_f32_dpp v164, v164, v164 quad_perm:[2,3,0,1] row_mask:0xf bank_mask:0xf bound_ctrl:1
	s_nop 1
	v_add_f32_dpp v164, v164, v164 row_half_mirror row_mask:0xf bank_mask:0xf bound_ctrl:1
	s_nop 1
	v_add_f32_dpp v174, v164, v164 row_mirror row_mask:0xf bank_mask:0xf bound_ctrl:1
	ds_bpermute_b32 v186, v96, v174
	s_and_saveexec_b64 s[42:43], s[6:7]
	s_cbranch_execz .LBB0_478
	s_lshl_b64 s[76:77], s[76:77], 6
	v_lshl_add_u64 v[164:165], v[68:69], 0, s[76:77]
	s_waitcnt lgkmcnt(0)
	v_add_f32_e32 v83, v174, v186
	global_store_dword v[164:165], v83, off
.LBB0_478:
	s_or_b64 exec, exec, s[42:43]
	s_nop 0
	v_lshlrev_b32_e32 v174, 16, v173
	s_nop 0
	v_sub_f32_e32 v21, v181, v174
	v_add_f32_e32 v83, v46, v184
	v_mul_f32_e32 v83, 0xbfb8aa3b, v83
	v_fma_f32 v181, v48, v21, v174
	v_add_f32_e32 v21, v47, v183
	v_exp_f32_e32 v83, v83
	v_mul_f32_e32 v21, 0xbfb8aa3b, v21
	v_exp_f32_e32 v21, v21
	v_and_b32_e32 v85, 0xffff0000, v173
	v_sub_f32_e32 v20, v20, v85
	v_fma_f32 v184, v49, v20, v85
	v_add_f32_e32 v20, 1.0, v83
	s_waitcnt lgkmcnt(1)
; __device__ __forceinline__ float bflo(unsigned u) { return __uint_as_float(u << 16); }
; __global__ void __launch_bounds__(NWAVES * 64, 2) mk_fwd(Args args) {
;     ...
;                     for (int tok = 0; tok < 16; ++tok) {
;                         const int m = m0 + tok;
;                         const unsigned ur = pur[tok + 1], uk = puk[tok + 1], uv = puv[tok + 1];
;                         const float cr[2] = {bflo(ur), bfhi(ur)}, ck[2] = {bflo(uk), bfhi(uk)}, cv[2] = {bflo(uv), bfhi(uv)};
;                         float rr[2], kk[2], vv[2], dec[2], aa[2], kkn[2], km[2], bb[2];
;                         rr[0] = cr[0] + (pr[0] - cr[0]) * mu_r.x; rr[1] = cr[1] + (pr[1] - cr[1]) * mu_r.y;
;                         kk[0] = ck[0] + (pk[0] - ck[0]) * mu_k.x; kk[1] = ck[1] + (pk[1] - ck[1]) * mu_k.y;
;                         vv[0] = cv[0] + (pv[0] - cv[0]) * mu_v.x; vv[1] = cv[1] + (pv[1] - cv[1]) * mu_v.y;
;                         dec[0] = __expf(-0.6065306597126334f * sigmoidf_(w0v.x + lw[tok][0])); dec[1] = __expf(-0.6065306597126334f * sigmoidf_(w0v.y + lw[tok][1]));
;                         aa[0] = sigmoidf_(a0v.x + la[tok][0]); aa[1] = sigmoidf_(a0v.y + la[tok][1]);
;                         kkn[0] = kk[0] * kkw.x; kkn[1] = kk[1] * kkw.y;
;                         const float ssq = sum32(kkn[0] * kkn[0] + kkn[1] * kkn[1]);
;                         const float inv = rsqrtf(ssq + 1e-12f);
;                         kkn[0] *= inv; kkn[1] *= inv;
;                         km[0] = kk[0] * (1.f + (aa[0] - 1.f) * kaw.x); km[1] = kk[1] * (1.f + (aa[1] - 1.f) * kaw.y);
;                         bb[0] = kkn[0] * aa[0]; bb[1] = kkn[1] * aa[1];
;                         const float rkd = sum32(rr[0] * km[0] * rkw.x + rr[1] * km[1] * rkw.y);
;                         if (kp == 0) rkdot[(size_t)m * 16 + h] = rkd;
;                         char* rec = scanrec + (rec0 + tok) * REC;
;                         *(f32x2*)(rec + kp * 8) = (f32x2){dec[0], dec[1]};
;                         *(f32x2*)(rec + 256 + kp * 8) = (f32x2){kkn[0], kkn[1]};
;                         *(f32x2*)(rec + 512 + kp * 8) = (f32x2){bb[0], bb[1]};
;                         *(unsigned*)(rec + 768 + kp * 4) = cvtpk(rr[0], rr[1]);
;                         *(unsigned*)(rec + 896 + kp * 4) = cvtpk(km[0], km[1]);
;                         *(unsigned*)(rec + 1024 + kp * 4) = cvtpk(vv[0], vv[1]);
	v_add_f32_e32 v83, v182, v185
	v_add_f32_e32 v21, 1.0, v21
	v_add_f32_e32 v83, 0x2b8cbccc, v83
	v_rcp_f32_e32 v20, v20
	v_rcp_f32_e32 v21, v21
	v_mul_f32_e32 v164, 0x4b800000, v83
	v_cmp_gt_f32_e32 vcc, s33, v83
	v_mul_f32_e32 v20, 0xbf1b4598, v20
	v_mul_f32_e32 v21, 0xbf1b4598, v21
	v_cndmask_b32_e32 v83, v83, v164, vcc
	v_rsq_f32_e32 v83, v83
	v_mul_f32_e32 v20, 0x3fb8aa3b, v20
	v_mul_f32_e32 v21, 0x3fb8aa3b, v21
	v_exp_f32_e32 v20, v20
	v_exp_f32_e32 v21, v21
	v_mul_f32_e32 v164, 0x45800000, v83
	v_cndmask_b32_e32 v164, v83, v164, vcc
	v_pk_mul_f32 v[30:31], v[30:31], v[164:165] op_sel_hi:[1,0]
	s_nop 0
	v_pk_mul_f32 v[80:81], v[80:81], v[30:31]
	s_nop 0
	global_store_dwordx2 v[24:25], v[20:21], off offset:1664
	global_store_dwordx2 v[24:25], v[30:31], off offset:1920
	global_store_dwordx2 v[24:25], v[80:81], off offset:2176
	v_add_f32_e32 v31, v44, v179
	v_add_f32_e32 v80, v45, v178
	v_mul_f32_e32 v31, 0xbfb8aa3b, v31
	v_mul_f32_e32 v80, 0xbfb8aa3b, v80
	v_cvt_pk_bf16_f32 v20, v175, v87
	v_exp_f32_e32 v31, v31
	v_exp_f32_e32 v80, v80
	global_store_dword v[28:29], v20, off offset:2432
	v_lshlrev_b32_e32 v20, 16, v161
	v_and_b32_e32 v21, 0xffff0000, v161
	v_and_b32_e32 v87, 0xffff0000, v162
	v_pk_add_f32 v[34:35], v[34:35], v[20:21] neg_lo:[0,1] neg_hi:[0,1]
	v_sub_f32_e32 v30, v86, v87
	v_pk_fma_f32 v[164:165], v[50:51], v[34:35], v[20:21]
	v_fma_f32 v81, v53, v30, v87
	v_add_f32_e32 v30, 1.0, v31
	v_add_f32_e32 v31, 1.0, v80
	v_pk_mul_f32 v[34:35], v[42:43], v[164:165]
	v_rcp_f32_e32 v31, v31
	v_pk_mul_f32 v[178:179], v[34:35], v[34:35]
	v_rcp_f32_e32 v30, v30
	v_add_f32_e32 v80, v178, v179
	v_add_f32_e32 v83, -1.0, v31
	v_lshlrev_b32_e32 v173, 16, v162
	v_add_f32_dpp v80, v80, v80 quad_perm:[1,0,3,2] row_mask:0xf bank_mask:0xf bound_ctrl:1
	v_fma_f32 v83, v41, v83, 1.0
	v_sub_f32_e32 v26, v180, v173
	v_add_f32_dpp v80, v80, v80 quad_perm:[2,3,0,1] row_mask:0xf bank_mask:0xf bound_ctrl:1
	v_mul_f32_e32 v83, v165, v83
	v_fma_f32 v26, v52, v26, v173
	v_add_f32_dpp v80, v80, v80 row_half_mirror row_mask:0xf bank_mask:0xf bound_ctrl:1
	v_cvt_pk_bf16_f32 v82, v82, v84
	global_store_dword v[28:29], v82, off offset:2560
	v_cvt_pk_bf16_f32 v82, v181, v184
	global_store_dword v[28:29], v82, off offset:2688
	v_add_f32_dpp v86, v80, v80 row_mirror row_mask:0xf bank_mask:0xf bound_ctrl:1
	v_add_f32_e32 v80, -1.0, v30
	v_fma_f32 v80, v40, v80, 1.0
	v_mul_f32_e32 v80, v164, v80
	v_mul_f32_e32 v164, v81, v83
	v_mul_f32_e32 v162, v26, v80
	v_mul_f32_e32 v164, v39, v164
	v_fmac_f32_e32 v164, v38, v162
	ds_bpermute_b32 v161, v96, v86
	s_nop 0
	v_add_f32_dpp v162, v164, v164 quad_perm:[1,0,3,2] row_mask:0xf bank_mask:0xf bound_ctrl:1
	s_nop 1
	v_add_f32_dpp v162, v162, v162 quad_perm:[2,3,0,1] row_mask:0xf bank_mask:0xf bound_ctrl:1
	s_nop 1
	v_add_f32_dpp v162, v162, v162 row_half_mirror row_mask:0xf bank_mask:0xf bound_ctrl:1
	s_nop 1
	v_add_f32_dpp v162, v162, v162 row_mirror row_mask:0xf bank_mask:0xf bound_ctrl:1
	ds_bpermute_b32 v175, v96, v162
	s_and_saveexec_b64 s[42:43], s[6:7]
	s_cbranch_execz .LBB0_480
	s_lshl_b64 s[74:75], s[74:75], 6
	v_lshl_add_u64 v[164:165], v[68:69], 0, s[74:75]
	s_waitcnt lgkmcnt(0)
	v_add_f32_e32 v82, v162, v175
	global_store_dword v[164:165], v82, off
.LBB0_480:
	s_or_b64 exec, exec, s[42:43]
	s_nop 0
	s_nop 0
	v_lshlrev_b32_e32 v84, 16, v158
	v_and_b32_e32 v22, 0xffff0000, v158
	v_add_f32_e32 v158, v46, v177
	v_mul_f32_e32 v158, 0xbfb8aa3b, v158
	v_exp_f32_e32 v158, v158
	v_sub_f32_e32 v82, v174, v84
	v_fma_f32 v174, v48, v82, v84
	v_sub_f32_e32 v82, v85, v22
	s_waitcnt lgkmcnt(0)
	v_fma_f32 v175, v49, v82, v22
	v_add_f32_e32 v82, 1.0, v158
	v_rcp_f32_e32 v82, v82
	v_add_f32_e32 v85, v47, v176
	v_mul_f32_e32 v85, 0xbfb8aa3b, v85
	v_exp_f32_e32 v85, v85
	v_mul_f32_e32 v82, 0xbf1b4598, v82
	v_mul_f32_e32 v82, 0x3fb8aa3b, v82
	v_exp_f32_e32 v164, v82
	v_add_f32_e32 v82, 1.0, v85
	v_add_f32_e32 v85, v86, v161
	v_add_f32_e32 v85, 0x2b8cbccc, v85
	v_rcp_f32_e32 v82, v82
	v_mul_f32_e32 v86, 0x4b800000, v85
	v_cmp_gt_f32_e32 vcc, s33, v85
	s_nop 0
	v_mul_f32_e32 v82, 0xbf1b4598, v82
	v_cndmask_b32_e32 v85, v85, v86, vcc
	v_rsq_f32_e32 v85, v85
	v_mul_f32_e32 v82, 0x3fb8aa3b, v82
	v_exp_f32_e32 v165, v82
	s_nop 0
	v_mul_f32_e32 v82, 0x45800000, v85
	v_cndmask_b32_e32 v82, v85, v82, vcc
	v_pk_mul_f32 v[34:35], v[34:35], v[82:83] op_sel_hi:[1,0]
	v_lshlrev_b32_e32 v82, 16, v156
	v_pk_mul_f32 v[30:31], v[30:31], v[34:35]
	global_store_dwordx2 v[24:25], v[164:165], off offset:2816
	global_store_dwordx2 v[24:25], v[34:35], off offset:3072
	global_store_dwordx2 v[24:25], v[30:31], off offset:3328
	v_add_f32_e32 v31, v44, v172
	v_mul_f32_e32 v31, 0xbfb8aa3b, v31
	v_exp_f32_e32 v31, v31
	v_add_f32_e32 v34, v45, v163
	v_mul_f32_e32 v34, 0xbfb8aa3b, v34
	v_cvt_pk_bf16_f32 v26, v26, v81
	v_and_b32_e32 v81, 0xffff0000, v156
	v_sub_f32_e32 v30, v173, v82
	v_exp_f32_e32 v34, v34
	v_fma_f32 v85, v52, v30, v82
	v_sub_f32_e32 v30, v87, v81
	v_fma_f32 v86, v53, v30, v81
	v_add_f32_e32 v30, 1.0, v31
	v_rcp_f32_e32 v30, v30
	v_add_f32_e32 v31, 1.0, v34
	v_rcp_f32_e32 v31, v31
	global_store_dword v[28:29], v26, off offset:3584
	v_lshlrev_b32_e32 v26, 16, v155
	v_and_b32_e32 v27, 0xffff0000, v155
	v_pk_add_f32 v[20:21], v[20:21], v[26:27] neg_lo:[0,1] neg_hi:[0,1]
	v_add_f32_e32 v156, -1.0, v30
	v_pk_fma_f32 v[34:35], v[50:51], v[20:21], v[26:27]
	v_fma_f32 v156, v40, v156, 1.0
	v_pk_mul_f32 v[20:21], v[42:43], v[34:35]
	v_mul_f32_e32 v34, v34, v156
	v_add_f32_e32 v156, -1.0, v31
	v_fma_f32 v156, v41, v156, 1.0
	v_mul_f32_e32 v35, v35, v156
	v_mul_f32_e32 v158, v86, v35
	v_pk_mul_f32 v[162:163], v[20:21], v[20:21]
	v_mul_f32_e32 v156, v85, v34
	v_mul_f32_e32 v158, v39, v158
	v_add_f32_e32 v87, v162, v163
	v_fmac_f32_e32 v158, v38, v156
	v_cvt_pk_bf16_f32 v80, v80, v83
	global_store_dword v[28:29], v80, off offset:3712
	v_add_f32_dpp v87, v87, v87 quad_perm:[1,0,3,2] row_mask:0xf bank_mask:0xf bound_ctrl:1
	v_add_f32_dpp v156, v158, v158 quad_perm:[1,0,3,2] row_mask:0xf bank_mask:0xf bound_ctrl:1
	v_cvt_pk_bf16_f32 v80, v174, v175
	global_store_dword v[28:29], v80, off offset:3840
	v_add_f32_dpp v87, v87, v87 quad_perm:[2,3,0,1] row_mask:0xf bank_mask:0xf bound_ctrl:1
	v_add_f32_dpp v156, v156, v156 quad_perm:[2,3,0,1] row_mask:0xf bank_mask:0xf bound_ctrl:1
	s_nop 0
	v_add_f32_dpp v87, v87, v87 row_half_mirror row_mask:0xf bank_mask:0xf bound_ctrl:1
	v_add_f32_dpp v156, v156, v156 row_half_mirror row_mask:0xf bank_mask:0xf bound_ctrl:1
	s_nop 0
	v_add_f32_dpp v87, v87, v87 row_mirror row_mask:0xf bank_mask:0xf bound_ctrl:1
	v_add_f32_dpp v156, v156, v156 row_mirror row_mask:0xf bank_mask:0xf bound_ctrl:1
	ds_bpermute_b32 v155, v96, v87
	ds_bpermute_b32 v158, v96, v156
	s_and_saveexec_b64 s[42:43], s[6:7]
	s_cbranch_execz .LBB0_482
	s_lshl_b64 s[72:73], s[72:73], 6
	v_lshl_add_u64 v[28:29], v[68:69], 0, s[72:73]
	s_waitcnt lgkmcnt(0)
	v_add_f32_e32 v80, v156, v158
	global_store_dword v[28:29], v80, off
; __device__ __forceinline__ float bflo(unsigned u) { return __uint_as_float(u << 16); }
; __global__ void __launch_bounds__(NWAVES * 64, 2) mk_fwd(Args args) {
;     ...
;                     for (int tok = 0; tok < 16; ++tok) {
;                         const int m = m0 + tok;
;                         const unsigned ur = pur[tok + 1], uk = puk[tok + 1], uv = puv[tok + 1];
;                         const float cr[2] = {bflo(ur), bfhi(ur)}, ck[2] = {bflo(uk), bfhi(uk)}, cv[2] = {bflo(uv), bfhi(uv)};
;                         float rr[2], kk[2], vv[2], dec[2], aa[2], kkn[2], km[2], bb[2];
;                         rr[0] = cr[0] + (pr[0] - cr[0]) * mu_r.x; rr[1] = cr[1] + (pr[1] - cr[1]) * mu_r.y;
;                         kk[0] = ck[0] + (pk[0] - ck[0]) * mu_k.x; kk[1] = ck[1] + (pk[1] - ck[1]) * mu_k.y;
;                         vv[0] = cv[0] + (pv[0] - cv[0]) * mu_v.x; vv[1] = cv[1] + (pv[1] - cv[1]) * mu_v.y;
;                         dec[0] = __expf(-0.6065306597126334f * sigmoidf_(w0v.x + lw[tok][0])); dec[1] = __expf(-0.6065306597126334f * sigmoidf_(w0v.y + lw[tok][1]));
;                         aa[0] = sigmoidf_(a0v.x + la[tok][0]); aa[1] = sigmoidf_(a0v.y + la[tok][1]);
;                         kkn[0] = kk[0] * kkw.x; kkn[1] = kk[1] * kkw.y;
;                         const float ssq = sum32(kkn[0] * kkn[0] + kkn[1] * kkn[1]);
;                         const float inv = rsqrtf(ssq + 1e-12f);
;                         kkn[0] *= inv; kkn[1] *= inv;
;                         km[0] = kk[0] * (1.f + (aa[0] - 1.f) * kaw.x); km[1] = kk[1] * (1.f + (aa[1] - 1.f) * kaw.y);
;                         bb[0] = kkn[0] * aa[0]; bb[1] = kkn[1] * aa[1];
;                         const float rkd = sum32(rr[0] * km[0] * rkw.x + rr[1] * km[1] * rkw.y);
;                         if (kp == 0) rkdot[(size_t)m * 16 + h] = rkd;
;                         char* rec = scanrec + (rec0 + tok) * REC;
;                         *(f32x2*)(rec + kp * 8) = (f32x2){dec[0], dec[1]};
;                         *(f32x2*)(rec + 256 + kp * 8) = (f32x2){kkn[0], kkn[1]};
;                         *(f32x2*)(rec + 512 + kp * 8) = (f32x2){bb[0], bb[1]};
;                         *(unsigned*)(rec + 768 + kp * 4) = cvtpk(rr[0], rr[1]);
;                         *(unsigned*)(rec + 896 + kp * 4) = cvtpk(km[0], km[1]);
;                         *(unsigned*)(rec + 1024 + kp * 4) = cvtpk(vv[0], vv[1]);
.LBB0_482:
	s_or_b64 exec, exec, s[42:43]
	s_nop 0
	v_lshlrev_b32_e32 v83, 16, v151
	s_nop 0
	v_sub_f32_e32 v23, v84, v83
	v_add_f32_e32 v28, v46, v160
	v_and_b32_e32 v80, 0xffff0000, v151
	v_mul_f32_e32 v28, 0xbfb8aa3b, v28
	v_fma_f32 v151, v48, v23, v83
	v_add_f32_e32 v23, v47, v159
	v_exp_f32_e32 v28, v28
	v_mul_f32_e32 v23, 0xbfb8aa3b, v23
	v_exp_f32_e32 v23, v23
	v_sub_f32_e32 v22, v22, v80
	v_fma_f32 v156, v49, v22, v80
	v_add_f32_e32 v22, 1.0, v28
	s_waitcnt lgkmcnt(1)
	v_add_f32_e32 v28, v87, v155
	v_add_f32_e32 v23, 1.0, v23
	v_add_f32_e32 v28, 0x2b8cbccc, v28
	v_rcp_f32_e32 v22, v22
	v_rcp_f32_e32 v23, v23
	v_mul_f32_e32 v29, 0x4b800000, v28
	v_cmp_gt_f32_e32 vcc, s33, v28
	v_mul_f32_e32 v22, 0xbf1b4598, v22
	v_mul_f32_e32 v23, 0xbf1b4598, v23
	v_cndmask_b32_e32 v28, v28, v29, vcc
	v_rsq_f32_e32 v28, v28
	v_mul_f32_e32 v22, 0x3fb8aa3b, v22
	v_mul_f32_e32 v23, 0x3fb8aa3b, v23
	v_exp_f32_e32 v22, v22
	v_exp_f32_e32 v23, v23
	v_mul_f32_e32 v29, 0x45800000, v28
	v_cndmask_b32_e32 v28, v28, v29, vcc
	s_movk_i32 s42, 0x2000
	v_pk_mul_f32 v[28:29], v[20:21], v[28:29] op_sel_hi:[1,0]
	v_add_co_u32_e32 v20, vcc, s42, v78
	v_pk_mul_f32 v[30:31], v[30:31], v[28:29]
	s_nop 0
	s_nop 0
	v_addc_co_u32_e32 v21, vcc, 0, v79, vcc
	global_store_dwordx2 v[24:25], v[22:23], off offset:3968
	global_store_dwordx2 v[20:21], v[28:29], off offset:128
	global_store_dwordx2 v[20:21], v[30:31], off offset:384
	v_add_f32_e32 v29, v44, v157
	v_add_f32_e32 v30, v45, v154
	v_mul_f32_e32 v29, 0xbfb8aa3b, v29
	v_mul_f32_e32 v30, 0xbfb8aa3b, v30
	v_exp_f32_e32 v29, v29
	v_exp_f32_e32 v30, v30
	v_add_co_u32_e32 v22, vcc, s42, v32
	v_and_b32_e32 v84, 0xffff0000, v148
	v_lshlrev_b32_e32 v24, 16, v147
	v_and_b32_e32 v25, 0xffff0000, v147
	v_cvt_pk_bf16_f32 v16, v85, v86
	v_addc_co_u32_e32 v23, vcc, 0, v33, vcc
	v_lshlrev_b32_e32 v85, 16, v148
	v_sub_f32_e32 v28, v81, v84
	v_pk_add_f32 v[26:27], v[26:27], v[24:25] neg_lo:[0,1] neg_hi:[0,1]
	global_store_dword v[22:23], v16, off offset:640
	v_sub_f32_e32 v16, v82, v85
	v_fma_f32 v82, v53, v28, v84
	v_add_f32_e32 v28, 1.0, v29
	v_add_f32_e32 v29, 1.0, v30
	v_pk_fma_f32 v[30:31], v[50:51], v[26:27], v[24:25]
	v_rcp_f32_e32 v28, v28
	v_pk_mul_f32 v[26:27], v[42:43], v[30:31]
	v_rcp_f32_e32 v29, v29
	v_pk_mul_f32 v[86:87], v[26:27], v[26:27]
	v_fma_f32 v16, v52, v16, v85
	v_add_f32_e32 v81, v86, v87
	v_cvt_pk_bf16_f32 v34, v34, v35
	global_store_dword v[22:23], v34, off offset:768
	v_cvt_pk_bf16_f32 v34, v151, v156
	global_store_dword v[22:23], v34, off offset:896
	v_add_f32_dpp v81, v81, v81 quad_perm:[1,0,3,2] row_mask:0xf bank_mask:0xf bound_ctrl:1
	s_nop 1
	v_add_f32_dpp v81, v81, v81 quad_perm:[2,3,0,1] row_mask:0xf bank_mask:0xf bound_ctrl:1
	s_nop 1
	v_add_f32_dpp v81, v81, v81 row_half_mirror row_mask:0xf bank_mask:0xf bound_ctrl:1
	s_nop 1
	v_add_f32_dpp v86, v81, v81 row_mirror row_mask:0xf bank_mask:0xf bound_ctrl:1
	v_add_f32_e32 v81, -1.0, v28
	v_fma_f32 v81, v40, v81, 1.0
	v_mul_f32_e32 v30, v30, v81
	v_add_f32_e32 v81, -1.0, v29
	v_fma_f32 v81, v41, v81, 1.0
	v_mul_f32_e32 v31, v31, v81
	v_mul_f32_e32 v147, v82, v31
	v_mul_f32_e32 v81, v16, v30
	v_mul_f32_e32 v147, v39, v147
	v_fmac_f32_e32 v147, v38, v81
	ds_bpermute_b32 v87, v96, v86
	s_nop 0
	v_add_f32_dpp v81, v147, v147 quad_perm:[1,0,3,2] row_mask:0xf bank_mask:0xf bound_ctrl:1
	s_nop 1
	v_add_f32_dpp v81, v81, v81 quad_perm:[2,3,0,1] row_mask:0xf bank_mask:0xf bound_ctrl:1
	s_nop 1
	v_add_f32_dpp v81, v81, v81 row_half_mirror row_mask:0xf bank_mask:0xf bound_ctrl:1
	s_nop 1
	v_add_f32_dpp v81, v81, v81 row_mirror row_mask:0xf bank_mask:0xf bound_ctrl:1
	ds_bpermute_b32 v147, v96, v81
	s_and_saveexec_b64 s[42:43], s[6:7]
	s_cbranch_execz .LBB0_484
	s_lshl_b64 s[70:71], s[70:71], 6
	v_lshl_add_u64 v[34:35], v[68:69], 0, s[70:71]
	s_waitcnt lgkmcnt(0)
	v_add_f32_e32 v81, v81, v147
	global_store_dword v[34:35], v81, off
.LBB0_484:
	s_or_b64 exec, exec, s[42:43]
	s_nop 0
	v_lshlrev_b32_e32 v81, 16, v144
	s_nop 0
	v_and_b32_e32 v35, 0xffff0000, v144
	v_add_f32_e32 v34, v46, v153
	v_mul_f32_e32 v34, 0xbfb8aa3b, v34
	v_exp_f32_e32 v34, v34
	v_sub_f32_e32 v12, v83, v81
	v_fma_f32 v144, v48, v12, v81
	v_sub_f32_e32 v12, v80, v35
	s_waitcnt lgkmcnt(0)
	v_fma_f32 v147, v49, v12, v35
	v_add_f32_e32 v12, 1.0, v34
	v_rcp_f32_e32 v12, v12
	v_add_f32_e32 v34, v47, v152
	v_mul_f32_e32 v34, 0xbfb8aa3b, v34
	v_exp_f32_e32 v34, v34
	v_mul_f32_e32 v12, 0xbf1b4598, v12
	v_mul_f32_e32 v12, 0x3fb8aa3b, v12
	v_exp_f32_e32 v152, v12
	v_add_f32_e32 v12, 1.0, v34
	v_add_f32_e32 v34, v86, v87
	v_add_f32_e32 v34, 0x2b8cbccc, v34
	v_rcp_f32_e32 v12, v12
	v_mul_f32_e32 v80, 0x4b800000, v34
	v_cmp_gt_f32_e32 vcc, s33, v34
	s_nop 0
	v_mul_f32_e32 v12, 0xbf1b4598, v12
	v_cndmask_b32_e32 v34, v34, v80, vcc
	v_rsq_f32_e32 v34, v34
	v_mul_f32_e32 v12, 0x3fb8aa3b, v12
	v_exp_f32_e32 v153, v12
	s_nop 0
	v_mul_f32_e32 v12, 0x45800000, v34
	v_cndmask_b32_e32 v12, v34, v12, vcc
	v_pk_mul_f32 v[26:27], v[26:27], v[12:13] op_sel_hi:[1,0]
	v_lshlrev_b32_e32 v34, 16, v143
	v_pk_mul_f32 v[28:29], v[28:29], v[26:27]
	global_store_dwordx2 v[20:21], v[152:153], off offset:1024
	global_store_dwordx2 v[20:21], v[26:27], off offset:1280
	global_store_dwordx2 v[20:21], v[28:29], off offset:1536
	v_add_f32_e32 v27, v44, v150
	v_add_f32_e32 v28, v45, v149
	v_mul_f32_e32 v27, 0xbfb8aa3b, v27
	v_mul_f32_e32 v28, 0xbfb8aa3b, v28
	v_exp_f32_e32 v27, v27
	v_exp_f32_e32 v28, v28
	v_cvt_pk_bf16_f32 v12, v16, v82
	global_store_dword v[22:23], v12, off offset:1792
	v_and_b32_e32 v12, 0xffff0000, v143
	v_lshlrev_b32_e32 v16, 16, v142
	v_and_b32_e32 v17, 0xffff0000, v142
	v_sub_f32_e32 v26, v85, v34
	v_fma_f32 v82, v52, v26, v34
; __device__ __forceinline__ float bflo(unsigned u) { return __uint_as_float(u << 16); }
; __global__ void __launch_bounds__(NWAVES * 64, 2) mk_fwd(Args args) {
;     ...
;                     for (int tok = 0; tok < 16; ++tok) {
;                         const int m = m0 + tok;
;                         const unsigned ur = pur[tok + 1], uk = puk[tok + 1], uv = puv[tok + 1];
;                         const float cr[2] = {bflo(ur), bfhi(ur)}, ck[2] = {bflo(uk), bfhi(uk)}, cv[2] = {bflo(uv), bfhi(uv)};
;                         float rr[2], kk[2], vv[2], dec[2], aa[2], kkn[2], km[2], bb[2];
;                         rr[0] = cr[0] + (pr[0] - cr[0]) * mu_r.x; rr[1] = cr[1] + (pr[1] - cr[1]) * mu_r.y;
;                         kk[0] = ck[0] + (pk[0] - ck[0]) * mu_k.x; kk[1] = ck[1] + (pk[1] - ck[1]) * mu_k.y;
;                         vv[0] = cv[0] + (pv[0] - cv[0]) * mu_v.x; vv[1] = cv[1] + (pv[1] - cv[1]) * mu_v.y;
;                         dec[0] = __expf(-0.6065306597126334f * sigmoidf_(w0v.x + lw[tok][0])); dec[1] = __expf(-0.6065306597126334f * sigmoidf_(w0v.y + lw[tok][1]));
;                         aa[0] = sigmoidf_(a0v.x + la[tok][0]); aa[1] = sigmoidf_(a0v.y + la[tok][1]);
;                         kkn[0] = kk[0] * kkw.x; kkn[1] = kk[1] * kkw.y;
;                         const float ssq = sum32(kkn[0] * kkn[0] + kkn[1] * kkn[1]);
;                         const float inv = rsqrtf(ssq + 1e-12f);
;                         kkn[0] *= inv; kkn[1] *= inv;
;                         km[0] = kk[0] * (1.f + (aa[0] - 1.f) * kaw.x); km[1] = kk[1] * (1.f + (aa[1] - 1.f) * kaw.y);
;                         bb[0] = kkn[0] * aa[0]; bb[1] = kkn[1] * aa[1];
;                         const float rkd = sum32(rr[0] * km[0] * rkw.x + rr[1] * km[1] * rkw.y);
;                         if (kp == 0) rkdot[(size_t)m * 16 + h] = rkd;
;                         char* rec = scanrec + (rec0 + tok) * REC;
;                         *(f32x2*)(rec + kp * 8) = (f32x2){dec[0], dec[1]};
;                         *(f32x2*)(rec + 256 + kp * 8) = (f32x2){kkn[0], kkn[1]};
;                         *(f32x2*)(rec + 512 + kp * 8) = (f32x2){bb[0], bb[1]};
;                         *(unsigned*)(rec + 768 + kp * 4) = cvtpk(rr[0], rr[1]);
;                         *(unsigned*)(rec + 896 + kp * 4) = cvtpk(km[0], km[1]);
;                         *(unsigned*)(rec + 1024 + kp * 4) = cvtpk(vv[0], vv[1]);
	v_sub_f32_e32 v26, v84, v12
	v_pk_add_f32 v[24:25], v[24:25], v[16:17] neg_lo:[0,1] neg_hi:[0,1]
	v_fma_f32 v83, v53, v26, v12
	v_add_f32_e32 v26, 1.0, v27
	v_add_f32_e32 v27, 1.0, v28
	v_pk_fma_f32 v[28:29], v[50:51], v[24:25], v[16:17]
	v_rcp_f32_e32 v26, v26
	v_pk_mul_f32 v[24:25], v[42:43], v[28:29]
	v_rcp_f32_e32 v27, v27
	v_pk_mul_f32 v[84:85], v[24:25], v[24:25]
	v_cvt_pk_bf16_f32 v30, v30, v31
	global_store_dword v[22:23], v30, off offset:1920
	v_add_f32_e32 v80, v84, v85
	v_cvt_pk_bf16_f32 v30, v144, v147
	global_store_dword v[22:23], v30, off offset:2048
	s_nop 0
	v_add_f32_dpp v80, v80, v80 quad_perm:[1,0,3,2] row_mask:0xf bank_mask:0xf bound_ctrl:1
	s_nop 1
	v_add_f32_dpp v80, v80, v80 quad_perm:[2,3,0,1] row_mask:0xf bank_mask:0xf bound_ctrl:1
	s_nop 1
	v_add_f32_dpp v80, v80, v80 row_half_mirror row_mask:0xf bank_mask:0xf bound_ctrl:1
	s_nop 1
	v_add_f32_dpp v84, v80, v80 row_mirror row_mask:0xf bank_mask:0xf bound_ctrl:1
	v_add_f32_e32 v80, -1.0, v26
	v_fma_f32 v80, v40, v80, 1.0
	v_mul_f32_e32 v28, v28, v80
	v_add_f32_e32 v80, -1.0, v27
	v_fma_f32 v80, v41, v80, 1.0
	v_mul_f32_e32 v29, v29, v80
	v_mul_f32_e32 v86, v83, v29
	v_mul_f32_e32 v80, v82, v28
	v_mul_f32_e32 v86, v39, v86
	v_fmac_f32_e32 v86, v38, v80
	ds_bpermute_b32 v85, v96, v84
	s_nop 0
	v_add_f32_dpp v80, v86, v86 quad_perm:[1,0,3,2] row_mask:0xf bank_mask:0xf bound_ctrl:1
	s_nop 1
	v_add_f32_dpp v80, v80, v80 quad_perm:[2,3,0,1] row_mask:0xf bank_mask:0xf bound_ctrl:1
	s_nop 1
	v_add_f32_dpp v80, v80, v80 row_half_mirror row_mask:0xf bank_mask:0xf bound_ctrl:1
	s_nop 1
	v_add_f32_dpp v80, v80, v80 row_mirror row_mask:0xf bank_mask:0xf bound_ctrl:1
	ds_bpermute_b32 v86, v96, v80
	s_and_saveexec_b64 s[42:43], s[6:7]
	s_cbranch_execz .LBB0_486
	s_lshl_b64 s[68:69], s[68:69], 6
	v_lshl_add_u64 v[30:31], v[68:69], 0, s[68:69]
	s_waitcnt lgkmcnt(0)
	v_add_f32_e32 v80, v80, v86
	global_store_dword v[30:31], v80, off
.LBB0_486:
	s_or_b64 exec, exec, s[42:43]
	s_nop 0
	v_lshlrev_b32_e32 v80, 16, v138
	s_nop 0
	v_and_b32_e32 v30, 0xffff0000, v138
	v_add_f32_e32 v31, v46, v146
	v_mul_f32_e32 v31, 0xbfb8aa3b, v31
	v_exp_f32_e32 v31, v31
	v_sub_f32_e32 v13, v81, v80
	v_fma_f32 v138, v48, v13, v80
	v_sub_f32_e32 v13, v35, v30
	v_fma_f32 v142, v49, v13, v30
	v_add_f32_e32 v13, 1.0, v31
	v_rcp_f32_e32 v13, v13
	v_add_f32_e32 v31, v47, v145
	v_mul_f32_e32 v31, 0xbfb8aa3b, v31
	v_exp_f32_e32 v31, v31
	v_mul_f32_e32 v13, 0xbf1b4598, v13
	v_mul_f32_e32 v13, 0x3fb8aa3b, v13
	s_waitcnt lgkmcnt(0)
	v_exp_f32_e32 v86, v13
	v_add_f32_e32 v13, 1.0, v31
	v_add_f32_e32 v31, v84, v85
	v_rcp_f32_e32 v13, v13
	v_add_f32_e32 v31, 0x2b8cbccc, v31
	v_mul_f32_e32 v35, 0x4b800000, v31
	v_cmp_gt_f32_e32 vcc, s33, v31
	v_mul_f32_e32 v13, 0xbf1b4598, v13
	v_mul_f32_e32 v13, 0x3fb8aa3b, v13
	v_cndmask_b32_e32 v31, v31, v35, vcc
	v_rsq_f32_e32 v31, v31
	v_exp_f32_e32 v87, v13
	s_nop 0
	s_nop 0
	v_mul_f32_e32 v13, 0x45800000, v31
	v_cndmask_b32_e32 v84, v31, v13, vcc
	v_pk_mul_f32 v[24:25], v[24:25], v[84:85] op_sel_hi:[1,0]
	v_lshlrev_b32_e32 v31, 16, v137
	v_pk_mul_f32 v[26:27], v[26:27], v[24:25]
	global_store_dwordx2 v[20:21], v[86:87], off offset:2176
	global_store_dwordx2 v[20:21], v[24:25], off offset:2432
	global_store_dwordx2 v[20:21], v[26:27], off offset:2688
	v_cvt_pk_bf16_f32 v13, v82, v83
	global_store_dword v[22:23], v13, off offset:2944
	v_sub_f32_e32 v13, v34, v31
	v_fma_f32 v35, v52, v13, v31
	v_add_f32_e32 v13, v44, v122
	v_add_f32_e32 v26, v45, v141
	v_mul_f32_e32 v13, 0xbfb8aa3b, v13
	v_mul_f32_e32 v26, 0xbfb8aa3b, v26
	v_exp_f32_e32 v13, v13
	v_exp_f32_e32 v26, v26
	v_and_b32_e32 v18, 0xffff0000, v137
	v_lshlrev_b32_e32 v24, 16, v136
	v_and_b32_e32 v25, 0xffff0000, v136
	v_sub_f32_e32 v12, v12, v18
	v_pk_add_f32 v[16:17], v[16:17], v[24:25] neg_lo:[0,1] neg_hi:[0,1]
	v_fma_f32 v81, v53, v12, v18
	v_add_f32_e32 v12, 1.0, v13
	v_add_f32_e32 v13, 1.0, v26
	v_pk_fma_f32 v[26:27], v[50:51], v[16:17], v[24:25]
	v_rcp_f32_e32 v12, v12
	v_pk_mul_f32 v[16:17], v[42:43], v[26:27]
	v_rcp_f32_e32 v13, v13
	v_pk_mul_f32 v[82:83], v[16:17], v[16:17]
	v_cvt_pk_bf16_f32 v28, v28, v29
	global_store_dword v[22:23], v28, off offset:3072
	v_add_f32_e32 v34, v82, v83
	v_cvt_pk_bf16_f32 v28, v138, v142
	global_store_dword v[22:23], v28, off offset:3200
	s_nop 0
	v_add_f32_dpp v34, v34, v34 quad_perm:[1,0,3,2] row_mask:0xf bank_mask:0xf bound_ctrl:1
	s_nop 1
	v_add_f32_dpp v34, v34, v34 quad_perm:[2,3,0,1] row_mask:0xf bank_mask:0xf bound_ctrl:1
	s_nop 1
	v_add_f32_dpp v34, v34, v34 row_half_mirror row_mask:0xf bank_mask:0xf bound_ctrl:1
	s_nop 1
	v_add_f32_dpp v82, v34, v34 row_mirror row_mask:0xf bank_mask:0xf bound_ctrl:1
	v_add_f32_e32 v34, -1.0, v12
	v_fma_f32 v34, v40, v34, 1.0
	v_mul_f32_e32 v26, v26, v34
	v_add_f32_e32 v34, -1.0, v13
	v_fma_f32 v34, v41, v34, 1.0
	v_mul_f32_e32 v27, v27, v34
	v_mul_f32_e32 v84, v81, v27
	v_mul_f32_e32 v34, v35, v26
	v_mul_f32_e32 v84, v39, v84
	v_fmac_f32_e32 v84, v38, v34
	ds_bpermute_b32 v83, v96, v82
	s_nop 0
	v_add_f32_dpp v34, v84, v84 quad_perm:[1,0,3,2] row_mask:0xf bank_mask:0xf bound_ctrl:1
	s_nop 1
	v_add_f32_dpp v34, v34, v34 quad_perm:[2,3,0,1] row_mask:0xf bank_mask:0xf bound_ctrl:1
	s_nop 1
	v_add_f32_dpp v34, v34, v34 row_half_mirror row_mask:0xf bank_mask:0xf bound_ctrl:1
	s_nop 1
	v_add_f32_dpp v34, v34, v34 row_mirror row_mask:0xf bank_mask:0xf bound_ctrl:1
	ds_bpermute_b32 v84, v96, v34
	s_and_saveexec_b64 s[42:43], s[6:7]
	s_cbranch_execz .LBB0_488
	s_lshl_b64 s[66:67], s[66:67], 6
	v_lshl_add_u64 v[22:23], v[68:69], 0, s[66:67]
	s_waitcnt lgkmcnt(0)
	v_add_f32_e32 v28, v34, v84
	global_store_dword v[22:23], v28, off
; __device__ __forceinline__ float bflo(unsigned u) { return __uint_as_float(u << 16); }
; __global__ void __launch_bounds__(NWAVES * 64, 2) mk_fwd(Args args) {
;     ...
;                     for (int tok = 0; tok < 16; ++tok) {
;                         const int m = m0 + tok;
;                         const unsigned ur = pur[tok + 1], uk = puk[tok + 1], uv = puv[tok + 1];
;                         const float cr[2] = {bflo(ur), bfhi(ur)}, ck[2] = {bflo(uk), bfhi(uk)}, cv[2] = {bflo(uv), bfhi(uv)};
;                         float rr[2], kk[2], vv[2], dec[2], aa[2], kkn[2], km[2], bb[2];
;                         rr[0] = cr[0] + (pr[0] - cr[0]) * mu_r.x; rr[1] = cr[1] + (pr[1] - cr[1]) * mu_r.y;
;                         kk[0] = ck[0] + (pk[0] - ck[0]) * mu_k.x; kk[1] = ck[1] + (pk[1] - ck[1]) * mu_k.y;
;                         vv[0] = cv[0] + (pv[0] - cv[0]) * mu_v.x; vv[1] = cv[1] + (pv[1] - cv[1]) * mu_v.y;
;                         dec[0] = __expf(-0.6065306597126334f * sigmoidf_(w0v.x + lw[tok][0])); dec[1] = __expf(-0.6065306597126334f * sigmoidf_(w0v.y + lw[tok][1]));
;                         aa[0] = sigmoidf_(a0v.x + la[tok][0]); aa[1] = sigmoidf_(a0v.y + la[tok][1]);
;                         kkn[0] = kk[0] * kkw.x; kkn[1] = kk[1] * kkw.y;
;                         const float ssq = sum32(kkn[0] * kkn[0] + kkn[1] * kkn[1]);
;                         const float inv = rsqrtf(ssq + 1e-12f);
;                         kkn[0] *= inv; kkn[1] *= inv;
;                         km[0] = kk[0] * (1.f + (aa[0] - 1.f) * kaw.x); km[1] = kk[1] * (1.f + (aa[1] - 1.f) * kaw.y);
;                         bb[0] = kkn[0] * aa[0]; bb[1] = kkn[1] * aa[1];
;                         const float rkd = sum32(rr[0] * km[0] * rkw.x + rr[1] * km[1] * rkw.y);
;                         if (kp == 0) rkdot[(size_t)m * 16 + h] = rkd;
;                         char* rec = scanrec + (rec0 + tok) * REC;
;                         *(f32x2*)(rec + kp * 8) = (f32x2){dec[0], dec[1]};
;                         *(f32x2*)(rec + 256 + kp * 8) = (f32x2){kkn[0], kkn[1]};
;                         *(f32x2*)(rec + 512 + kp * 8) = (f32x2){bb[0], bb[1]};
;                         *(unsigned*)(rec + 768 + kp * 4) = cvtpk(rr[0], rr[1]);
;                         *(unsigned*)(rec + 896 + kp * 4) = cvtpk(km[0], km[1]);
;                         *(unsigned*)(rec + 1024 + kp * 4) = cvtpk(vv[0], vv[1]);
.LBB0_488:
	s_or_b64 exec, exec, s[42:43]
	s_nop 0
	v_lshlrev_b32_e32 v34, 16, v131
	s_nop 0
	v_and_b32_e32 v14, 0xffff0000, v131
	v_add_f32_e32 v23, v46, v140
	v_mul_f32_e32 v23, 0xbfb8aa3b, v23
	v_exp_f32_e32 v23, v23
	v_sub_f32_e32 v22, v80, v34
	s_waitcnt lgkmcnt(0)
	v_fma_f32 v84, v48, v22, v34
	v_sub_f32_e32 v22, v30, v14
	v_fma_f32 v85, v49, v22, v14
	v_add_f32_e32 v22, 1.0, v23
	v_add_f32_e32 v23, v47, v139
	v_mul_f32_e32 v23, 0xbfb8aa3b, v23
	v_exp_f32_e32 v23, v23
	v_add_f32_e32 v28, v82, v83
	v_add_f32_e32 v28, 0x2b8cbccc, v28
	v_mul_f32_e32 v29, 0x4b800000, v28
	v_add_f32_e32 v23, 1.0, v23
	v_cmp_gt_f32_e32 vcc, s33, v28
	v_rcp_f32_e32 v22, v22
	v_rcp_f32_e32 v23, v23
	v_cndmask_b32_e32 v28, v28, v29, vcc
	v_rsq_f32_e32 v28, v28
	v_mul_f32_e32 v22, 0xbf1b4598, v22
	v_mul_f32_e32 v23, 0xbf1b4598, v23
	v_mul_f32_e32 v22, 0x3fb8aa3b, v22
	v_mul_f32_e32 v23, 0x3fb8aa3b, v23
	v_mul_f32_e32 v29, 0x45800000, v28
	v_exp_f32_e32 v22, v22
	v_exp_f32_e32 v23, v23
	v_cndmask_b32_e32 v28, v28, v29, vcc
	v_pk_mul_f32 v[16:17], v[16:17], v[28:29] op_sel_hi:[1,0]
	v_lshlrev_b32_e32 v29, 16, v129
	s_nop 0
	s_nop 0
	v_sub_f32_e32 v19, v31, v29
	v_fma_f32 v30, v52, v19, v29
	v_add_f32_e32 v19, v44, v135
	v_pk_mul_f32 v[12:13], v[12:13], v[16:17]
	global_store_dwordx2 v[20:21], v[22:23], off offset:3328
	global_store_dwordx2 v[20:21], v[16:17], off offset:3584
	global_store_dwordx2 v[20:21], v[12:13], off offset:3840
	v_mul_f32_e32 v19, 0xbfb8aa3b, v19
	v_add_f32_e32 v20, v45, v134
	v_exp_f32_e32 v19, v19
	v_mul_f32_e32 v20, 0xbfb8aa3b, v20
	s_movk_i32 s42, 0x3000
	v_exp_f32_e32 v20, v20
	v_add_co_u32_e32 v12, vcc, s42, v32
	v_and_b32_e32 v28, 0xffff0000, v129
	v_cvt_pk_bf16_f32 v16, v35, v81
	s_nop 0
	v_addc_co_u32_e32 v13, vcc, 0, v33, vcc
	v_sub_f32_e32 v18, v18, v28
	global_store_dword v[12:13], v16, off
	v_lshlrev_b32_e32 v16, 16, v130
	v_and_b32_e32 v17, 0xffff0000, v130
	v_fma_f32 v35, v53, v18, v28
	v_add_f32_e32 v18, 1.0, v19
	v_rcp_f32_e32 v18, v18
	v_add_f32_e32 v19, 1.0, v20
	v_pk_add_f32 v[20:21], v[24:25], v[16:17] neg_lo:[0,1] neg_hi:[0,1]
	v_rcp_f32_e32 v19, v19
	v_pk_fma_f32 v[22:23], v[50:51], v[20:21], v[16:17]
	v_cvt_pk_bf16_f32 v26, v26, v27
	global_store_dword v[12:13], v26, off offset:128
	v_pk_mul_f32 v[20:21], v[42:43], v[22:23]
	v_cvt_pk_bf16_f32 v26, v84, v85
	global_store_dword v[12:13], v26, off offset:256
	v_pk_mul_f32 v[24:25], v[20:21], v[20:21]
	s_nop 0
	v_add_f32_e32 v24, v24, v25
	v_add_f32_e32 v25, -1.0, v18
	v_fma_f32 v25, v40, v25, 1.0
	v_mul_f32_e32 v22, v22, v25
	v_add_f32_e32 v25, -1.0, v19
	v_fma_f32 v25, v41, v25, 1.0
	v_mul_f32_e32 v23, v23, v25
	v_mul_f32_e32 v31, v35, v23
	v_mul_f32_e32 v25, v30, v22
	v_mul_f32_e32 v31, v39, v31
	v_fmac_f32_e32 v31, v38, v25
	v_add_f32_dpp v24, v24, v24 quad_perm:[1,0,3,2] row_mask:0xf bank_mask:0xf bound_ctrl:1
	s_nop 0
	v_add_f32_dpp v25, v31, v31 quad_perm:[1,0,3,2] row_mask:0xf bank_mask:0xf bound_ctrl:1
	v_add_f32_dpp v24, v24, v24 quad_perm:[2,3,0,1] row_mask:0xf bank_mask:0xf bound_ctrl:1
	s_nop 0
	v_add_f32_dpp v25, v25, v25 quad_perm:[2,3,0,1] row_mask:0xf bank_mask:0xf bound_ctrl:1
	v_add_f32_dpp v24, v24, v24 row_half_mirror row_mask:0xf bank_mask:0xf bound_ctrl:1
	s_nop 0
	v_add_f32_dpp v25, v25, v25 row_half_mirror row_mask:0xf bank_mask:0xf bound_ctrl:1
	v_add_f32_dpp v24, v24, v24 row_mirror row_mask:0xf bank_mask:0xf bound_ctrl:1
	ds_bpermute_b32 v80, v96, v24
	v_add_f32_dpp v25, v25, v25 row_mirror row_mask:0xf bank_mask:0xf bound_ctrl:1
	ds_bpermute_b32 v31, v96, v25
	s_and_saveexec_b64 s[42:43], s[6:7]
	s_cbranch_execz .LBB0_490
	s_lshl_b64 s[64:65], s[64:65], 6
	v_lshl_add_u64 v[26:27], v[68:69], 0, s[64:65]
	s_waitcnt lgkmcnt(0)
	v_add_f32_e32 v25, v25, v31
	global_store_dword v[26:27], v25, off
.LBB0_490:
	s_or_b64 exec, exec, s[42:43]
	s_nop 0
	v_and_b32_e32 v25, 0xffff0000, v125
	s_waitcnt lgkmcnt(0)
	v_lshlrev_b32_e32 v31, 16, v125
	v_sub_f32_e32 v14, v14, v25
	v_add_f32_e32 v26, v46, v133
	v_mul_f32_e32 v26, 0xbfb8aa3b, v26
	v_exp_f32_e32 v26, v26
	s_nop 0
	v_sub_f32_e32 v15, v34, v31
	v_fma_f32 v83, v49, v14, v25
	v_add_f32_e32 v14, 1.0, v26
	v_fma_f32 v82, v48, v15, v31
	v_rcp_f32_e32 v14, v14
	v_add_f32_e32 v15, v47, v132
	v_mul_f32_e32 v15, 0xbfb8aa3b, v15
	v_exp_f32_e32 v15, v15
	v_mul_f32_e32 v14, 0xbf1b4598, v14
	v_mul_f32_e32 v14, 0x3fb8aa3b, v14
	v_exp_f32_e32 v26, v14
	v_add_f32_e32 v14, 1.0, v15
	v_add_f32_e32 v15, v24, v80
	v_add_f32_e32 v15, 0x2b8cbccc, v15
	v_rcp_f32_e32 v14, v14
	v_mul_f32_e32 v24, 0x4b800000, v15
	v_cmp_gt_f32_e32 vcc, s33, v15
	s_movk_i32 s42, 0x3000
	v_mul_f32_e32 v14, 0xbf1b4598, v14
	v_cndmask_b32_e32 v15, v15, v24, vcc
	v_rsq_f32_e32 v15, v15
	v_mul_f32_e32 v14, 0x3fb8aa3b, v14
	v_exp_f32_e32 v27, v14
	s_nop 0
	v_mul_f32_e32 v14, 0x45800000, v15
	v_cndmask_b32_e32 v14, v15, v14, vcc
	v_pk_mul_f32 v[20:21], v[20:21], v[14:15] op_sel_hi:[1,0]
	v_add_co_u32_e32 v14, vcc, s42, v78
	s_nop 0
	s_nop 0
	v_addc_co_u32_e32 v15, vcc, 0, v79, vcc
	v_pk_mul_f32 v[18:19], v[18:19], v[20:21]
	global_store_dwordx2 v[14:15], v[26:27], off offset:384
	global_store_dwordx2 v[14:15], v[20:21], off offset:640
	global_store_dwordx2 v[14:15], v[18:19], off offset:896
	v_add_f32_e32 v21, v44, v128
	v_add_f32_e32 v24, v45, v126
	v_mul_f32_e32 v21, 0xbfb8aa3b, v21
	v_mul_f32_e32 v24, 0xbfb8aa3b, v24
	v_exp_f32_e32 v21, v21
	v_exp_f32_e32 v24, v24
	v_lshlrev_b32_e32 v18, 16, v120
	v_and_b32_e32 v19, 0xffff0000, v120
	v_and_b32_e32 v27, 0xffff0000, v121
	v_pk_add_f32 v[16:17], v[16:17], v[18:19] neg_lo:[0,1] neg_hi:[0,1]
	v_sub_f32_e32 v20, v28, v27
	v_pk_fma_f32 v[80:81], v[50:51], v[16:17], v[18:19]
	v_fma_f32 v28, v53, v20, v27
; __device__ __forceinline__ float bflo(unsigned u) { return __uint_as_float(u << 16); }
; __global__ void __launch_bounds__(NWAVES * 64, 2) mk_fwd(Args args) {
;     ...
;                     for (int tok = 0; tok < 16; ++tok) {
;                         const int m = m0 + tok;
;                         const unsigned ur = pur[tok + 1], uk = puk[tok + 1], uv = puv[tok + 1];
;                         const float cr[2] = {bflo(ur), bfhi(ur)}, ck[2] = {bflo(uk), bfhi(uk)}, cv[2] = {bflo(uv), bfhi(uv)};
;                         float rr[2], kk[2], vv[2], dec[2], aa[2], kkn[2], km[2], bb[2];
;                         rr[0] = cr[0] + (pr[0] - cr[0]) * mu_r.x; rr[1] = cr[1] + (pr[1] - cr[1]) * mu_r.y;
;                         kk[0] = ck[0] + (pk[0] - ck[0]) * mu_k.x; kk[1] = ck[1] + (pk[1] - ck[1]) * mu_k.y;
;                         vv[0] = cv[0] + (pv[0] - cv[0]) * mu_v.x; vv[1] = cv[1] + (pv[1] - cv[1]) * mu_v.y;
;                         dec[0] = __expf(-0.6065306597126334f * sigmoidf_(w0v.x + lw[tok][0])); dec[1] = __expf(-0.6065306597126334f * sigmoidf_(w0v.y + lw[tok][1]));
;                         aa[0] = sigmoidf_(a0v.x + la[tok][0]); aa[1] = sigmoidf_(a0v.y + la[tok][1]);
;                         kkn[0] = kk[0] * kkw.x; kkn[1] = kk[1] * kkw.y;
;                         const float ssq = sum32(kkn[0] * kkn[0] + kkn[1] * kkn[1]);
;                         const float inv = rsqrtf(ssq + 1e-12f);
;                         kkn[0] *= inv; kkn[1] *= inv;
;                         km[0] = kk[0] * (1.f + (aa[0] - 1.f) * kaw.x); km[1] = kk[1] * (1.f + (aa[1] - 1.f) * kaw.y);
;                         bb[0] = kkn[0] * aa[0]; bb[1] = kkn[1] * aa[1];
;                         const float rkd = sum32(rr[0] * km[0] * rkw.x + rr[1] * km[1] * rkw.y);
;                         if (kp == 0) rkdot[(size_t)m * 16 + h] = rkd;
;                         char* rec = scanrec + (rec0 + tok) * REC;
;                         *(f32x2*)(rec + kp * 8) = (f32x2){dec[0], dec[1]};
;                         *(f32x2*)(rec + 256 + kp * 8) = (f32x2){kkn[0], kkn[1]};
;                         *(f32x2*)(rec + 512 + kp * 8) = (f32x2){bb[0], bb[1]};
;                         *(unsigned*)(rec + 768 + kp * 4) = cvtpk(rr[0], rr[1]);
;                         *(unsigned*)(rec + 896 + kp * 4) = cvtpk(km[0], km[1]);
;                         *(unsigned*)(rec + 1024 + kp * 4) = cvtpk(vv[0], vv[1]);
	v_add_f32_e32 v20, 1.0, v21
	v_add_f32_e32 v21, 1.0, v24
	v_pk_mul_f32 v[16:17], v[42:43], v[80:81]
	v_cvt_pk_bf16_f32 v8, v30, v35
	v_rcp_f32_e32 v21, v21
	v_pk_mul_f32 v[34:35], v[16:17], v[16:17]
	v_rcp_f32_e32 v20, v20
	v_add_f32_e32 v24, v34, v35
	v_add_f32_e32 v26, -1.0, v21
	v_lshlrev_b32_e32 v30, 16, v121
	v_add_f32_dpp v24, v24, v24 quad_perm:[1,0,3,2] row_mask:0xf bank_mask:0xf bound_ctrl:1
	v_fma_f32 v26, v41, v26, 1.0
	global_store_dword v[12:13], v8, off offset:1152
	v_add_f32_dpp v24, v24, v24 quad_perm:[2,3,0,1] row_mask:0xf bank_mask:0xf bound_ctrl:1
	v_sub_f32_e32 v8, v29, v30
	v_mul_f32_e32 v26, v81, v26
	v_add_f32_dpp v24, v24, v24 row_half_mirror row_mask:0xf bank_mask:0xf bound_ctrl:1
	v_fma_f32 v8, v52, v8, v30
	v_cvt_pk_bf16_f32 v22, v22, v23
	global_store_dword v[12:13], v22, off offset:1280
	v_add_f32_dpp v34, v24, v24 row_mirror row_mask:0xf bank_mask:0xf bound_ctrl:1
	v_add_f32_e32 v24, -1.0, v20
	v_fma_f32 v24, v40, v24, 1.0
	v_mul_f32_e32 v24, v80, v24
	v_mul_f32_e32 v80, v28, v26
	v_mul_f32_e32 v29, v8, v24
	v_mul_f32_e32 v80, v39, v80
	v_fmac_f32_e32 v80, v38, v29
	ds_bpermute_b32 v35, v96, v34
	v_cvt_pk_bf16_f32 v22, v82, v83
	global_store_dword v[12:13], v22, off offset:1408
	v_add_f32_dpp v29, v80, v80 quad_perm:[1,0,3,2] row_mask:0xf bank_mask:0xf bound_ctrl:1
	s_nop 1
	v_add_f32_dpp v29, v29, v29 quad_perm:[2,3,0,1] row_mask:0xf bank_mask:0xf bound_ctrl:1
	s_nop 1
	v_add_f32_dpp v29, v29, v29 row_half_mirror row_mask:0xf bank_mask:0xf bound_ctrl:1
	s_nop 1
	v_add_f32_dpp v29, v29, v29 row_mirror row_mask:0xf bank_mask:0xf bound_ctrl:1
	ds_bpermute_b32 v80, v96, v29
	s_and_saveexec_b64 s[42:43], s[6:7]
	s_cbranch_execz .LBB0_492
	s_lshl_b64 s[62:63], s[62:63], 6
	v_lshl_add_u64 v[22:23], v[68:69], 0, s[62:63]
	s_waitcnt lgkmcnt(0)
	v_add_f32_e32 v29, v29, v80
	global_store_dword v[22:23], v29, off
.LBB0_492:
	s_or_b64 exec, exec, s[42:43]
	s_nop 0
	v_lshlrev_b32_e32 v29, 16, v117
	s_nop 0
	v_and_b32_e32 v4, 0xffff0000, v117
	v_add_f32_e32 v23, v46, v124
	v_mul_f32_e32 v23, 0xbfb8aa3b, v23
	v_exp_f32_e32 v23, v23
	v_sub_f32_e32 v22, v31, v29
	s_waitcnt lgkmcnt(0)
	v_fma_f32 v80, v48, v22, v29
	v_sub_f32_e32 v22, v25, v4
	v_fma_f32 v81, v49, v22, v4
	v_add_f32_e32 v22, 1.0, v23
	v_add_f32_e32 v23, v47, v123
	v_mul_f32_e32 v23, 0xbfb8aa3b, v23
	v_exp_f32_e32 v23, v23
	v_add_f32_e32 v25, v34, v35
	v_rcp_f32_e32 v22, v22
	v_add_f32_e32 v25, 0x2b8cbccc, v25
	v_add_f32_e32 v23, 1.0, v23
	v_rcp_f32_e32 v23, v23
	v_mul_f32_e32 v31, 0x4b800000, v25
	v_cmp_gt_f32_e32 vcc, s33, v25
	v_mul_f32_e32 v22, 0xbf1b4598, v22
	v_mul_f32_e32 v23, 0xbf1b4598, v23
	v_cndmask_b32_e32 v25, v25, v31, vcc
	v_rsq_f32_e32 v25, v25
	v_mul_f32_e32 v22, 0x3fb8aa3b, v22
	v_mul_f32_e32 v23, 0x3fb8aa3b, v23
	v_exp_f32_e32 v22, v22
	v_exp_f32_e32 v23, v23
	v_mul_f32_e32 v31, 0x45800000, v25
	v_cndmask_b32_e32 v34, v25, v31, vcc
	v_pk_mul_f32 v[16:17], v[16:17], v[34:35] op_sel_hi:[1,0]
	s_nop 0
	v_pk_mul_f32 v[20:21], v[20:21], v[16:17]
	s_nop 0
	global_store_dwordx2 v[14:15], v[22:23], off offset:1536
	global_store_dwordx2 v[14:15], v[16:17], off offset:1792
	global_store_dwordx2 v[14:15], v[20:21], off offset:2048
	v_add_f32_e32 v17, v44, v119
	v_cvt_pk_bf16_f32 v8, v8, v28
	v_mul_f32_e32 v17, 0xbfb8aa3b, v17
	v_add_f32_e32 v20, v45, v118
	global_store_dword v[12:13], v8, off offset:2304
	v_lshlrev_b32_e32 v8, 16, v113
	v_and_b32_e32 v9, 0xffff0000, v113
	v_exp_f32_e32 v17, v17
	v_mul_f32_e32 v20, 0xbfb8aa3b, v20
	v_lshlrev_b32_e32 v28, 16, v114
	v_exp_f32_e32 v20, v20
	v_pk_add_f32 v[18:19], v[18:19], v[8:9] neg_lo:[0,1] neg_hi:[0,1]
	v_and_b32_e32 v25, 0xffff0000, v114
	v_sub_f32_e32 v16, v30, v28
	v_pk_fma_f32 v[22:23], v[50:51], v[18:19], v[8:9]
	v_fma_f32 v21, v52, v16, v28
	v_sub_f32_e32 v16, v27, v25
	v_pk_mul_f32 v[18:19], v[42:43], v[22:23]
	v_fma_f32 v27, v53, v16, v25
	v_add_f32_e32 v16, 1.0, v17
	v_pk_mul_f32 v[30:31], v[18:19], v[18:19]
	v_rcp_f32_e32 v16, v16
	v_add_f32_e32 v17, 1.0, v20
	v_add_f32_e32 v20, v30, v31
	v_rcp_f32_e32 v17, v17
	v_cvt_pk_bf16_f32 v24, v24, v26
	global_store_dword v[12:13], v24, off offset:2432
	v_add_f32_dpp v20, v20, v20 quad_perm:[1,0,3,2] row_mask:0xf bank_mask:0xf bound_ctrl:1
	v_cvt_pk_bf16_f32 v24, v80, v81
	global_store_dword v[12:13], v24, off offset:2560
	s_nop 0
	v_add_f32_dpp v20, v20, v20 quad_perm:[2,3,0,1] row_mask:0xf bank_mask:0xf bound_ctrl:1
	s_nop 1
	v_add_f32_dpp v20, v20, v20 row_half_mirror row_mask:0xf bank_mask:0xf bound_ctrl:1
	s_nop 1
	v_add_f32_dpp v30, v20, v20 row_mirror row_mask:0xf bank_mask:0xf bound_ctrl:1
	v_add_f32_e32 v20, -1.0, v16
	v_fma_f32 v20, v40, v20, 1.0
	v_mul_f32_e32 v20, v22, v20
	v_add_f32_e32 v22, -1.0, v17
	v_fma_f32 v22, v41, v22, 1.0
	v_mul_f32_e32 v22, v23, v22
	v_mul_f32_e32 v34, v27, v22
	v_mul_f32_e32 v23, v21, v20
	v_mul_f32_e32 v34, v39, v34
	v_fmac_f32_e32 v34, v38, v23
	ds_bpermute_b32 v31, v96, v30
	s_nop 0
	v_add_f32_dpp v23, v34, v34 quad_perm:[1,0,3,2] row_mask:0xf bank_mask:0xf bound_ctrl:1
	s_nop 1
	v_add_f32_dpp v23, v23, v23 quad_perm:[2,3,0,1] row_mask:0xf bank_mask:0xf bound_ctrl:1
	s_nop 1
	v_add_f32_dpp v23, v23, v23 row_half_mirror row_mask:0xf bank_mask:0xf bound_ctrl:1
	s_nop 1
	v_add_f32_dpp v23, v23, v23 row_mirror row_mask:0xf bank_mask:0xf bound_ctrl:1
	ds_bpermute_b32 v34, v96, v23
	s_and_saveexec_b64 s[42:43], s[6:7]
	s_cbranch_execz .LBB0_494
	s_lshl_b64 s[60:61], s[60:61], 6
	v_lshl_add_u64 v[80:81], v[68:69], 0, s[60:61]
	s_waitcnt lgkmcnt(0)
	v_add_f32_e32 v23, v23, v34
	global_store_dword v[80:81], v23, off
; __device__ __forceinline__ float bflo(unsigned u) { return __uint_as_float(u << 16); }
; __global__ void __launch_bounds__(NWAVES * 64, 2) mk_fwd(Args args) {
;     ...
;                     for (int tok = 0; tok < 16; ++tok) {
;                         const int m = m0 + tok;
;                         const unsigned ur = pur[tok + 1], uk = puk[tok + 1], uv = puv[tok + 1];
;                         const float cr[2] = {bflo(ur), bfhi(ur)}, ck[2] = {bflo(uk), bfhi(uk)}, cv[2] = {bflo(uv), bfhi(uv)};
;                         float rr[2], kk[2], vv[2], dec[2], aa[2], kkn[2], km[2], bb[2];
;                         rr[0] = cr[0] + (pr[0] - cr[0]) * mu_r.x; rr[1] = cr[1] + (pr[1] - cr[1]) * mu_r.y;
;                         kk[0] = ck[0] + (pk[0] - ck[0]) * mu_k.x; kk[1] = ck[1] + (pk[1] - ck[1]) * mu_k.y;
;                         vv[0] = cv[0] + (pv[0] - cv[0]) * mu_v.x; vv[1] = cv[1] + (pv[1] - cv[1]) * mu_v.y;
;                         dec[0] = __expf(-0.6065306597126334f * sigmoidf_(w0v.x + lw[tok][0])); dec[1] = __expf(-0.6065306597126334f * sigmoidf_(w0v.y + lw[tok][1]));
;                         aa[0] = sigmoidf_(a0v.x + la[tok][0]); aa[1] = sigmoidf_(a0v.y + la[tok][1]);
;                         kkn[0] = kk[0] * kkw.x; kkn[1] = kk[1] * kkw.y;
;                         const float ssq = sum32(kkn[0] * kkn[0] + kkn[1] * kkn[1]);
;                         const float inv = rsqrtf(ssq + 1e-12f);
;                         kkn[0] *= inv; kkn[1] *= inv;
;                         km[0] = kk[0] * (1.f + (aa[0] - 1.f) * kaw.x); km[1] = kk[1] * (1.f + (aa[1] - 1.f) * kaw.y);
;                         bb[0] = kkn[0] * aa[0]; bb[1] = kkn[1] * aa[1];
;                         const float rkd = sum32(rr[0] * km[0] * rkw.x + rr[1] * km[1] * rkw.y);
;                         if (kp == 0) rkdot[(size_t)m * 16 + h] = rkd;
;                         char* rec = scanrec + (rec0 + tok) * REC;
;                         *(f32x2*)(rec + kp * 8) = (f32x2){dec[0], dec[1]};
;                         *(f32x2*)(rec + 256 + kp * 8) = (f32x2){kkn[0], kkn[1]};
;                         *(f32x2*)(rec + 512 + kp * 8) = (f32x2){bb[0], bb[1]};
;                         *(unsigned*)(rec + 768 + kp * 4) = cvtpk(rr[0], rr[1]);
;                         *(unsigned*)(rec + 896 + kp * 4) = cvtpk(km[0], km[1]);
;                         *(unsigned*)(rec + 1024 + kp * 4) = cvtpk(vv[0], vv[1]);
.LBB0_494:
	s_or_b64 exec, exec, s[42:43]
	s_nop 0
	v_lshlrev_b32_e32 v24, 16, v110
	s_nop 0
	v_sub_f32_e32 v5, v29, v24
	v_add_f32_e32 v26, v46, v116
	v_mul_f32_e32 v26, 0xbfb8aa3b, v26
	s_waitcnt lgkmcnt(0)
	v_fma_f32 v34, v48, v5, v24
	v_add_f32_e32 v5, v47, v115
	v_exp_f32_e32 v26, v26
	v_mul_f32_e32 v5, 0xbfb8aa3b, v5
	v_exp_f32_e32 v5, v5
	v_and_b32_e32 v23, 0xffff0000, v110
	v_sub_f32_e32 v4, v4, v23
	v_fma_f32 v35, v49, v4, v23
	v_add_f32_e32 v4, 1.0, v26
	v_add_f32_e32 v26, v30, v31
	v_add_f32_e32 v5, 1.0, v5
	v_add_f32_e32 v26, 0x2b8cbccc, v26
	v_rcp_f32_e32 v4, v4
	v_rcp_f32_e32 v5, v5
	v_mul_f32_e32 v29, 0x4b800000, v26
	v_cmp_gt_f32_e32 vcc, s33, v26
	v_mul_f32_e32 v4, 0xbf1b4598, v4
	v_mul_f32_e32 v5, 0xbf1b4598, v5
	v_cndmask_b32_e32 v26, v26, v29, vcc
	v_rsq_f32_e32 v26, v26
	v_mul_f32_e32 v4, 0x3fb8aa3b, v4
	v_mul_f32_e32 v5, 0x3fb8aa3b, v5
	v_exp_f32_e32 v4, v4
	v_exp_f32_e32 v5, v5
	v_mul_f32_e32 v29, 0x45800000, v26
	v_cndmask_b32_e32 v26, v26, v29, vcc
	v_pk_mul_f32 v[18:19], v[18:19], v[26:27] op_sel_hi:[1,0]
	s_nop 0
	v_pk_mul_f32 v[16:17], v[16:17], v[18:19]
	global_store_dwordx2 v[14:15], v[4:5], off offset:2688
	global_store_dwordx2 v[14:15], v[18:19], off offset:2944
	global_store_dwordx2 v[14:15], v[16:17], off offset:3200
	v_add_f32_e32 v17, v44, v112
	s_nop 0
	v_mul_f32_e32 v17, 0xbfb8aa3b, v17
	v_exp_f32_e32 v17, v17
	v_cvt_pk_bf16_f32 v4, v21, v27
	v_lshlrev_b32_e32 v21, 16, v106
	v_add_f32_e32 v18, v45, v111
	v_mul_f32_e32 v18, 0xbfb8aa3b, v18
	v_and_b32_e32 v10, 0xffff0000, v106
	v_sub_f32_e32 v16, v28, v21
	v_exp_f32_e32 v18, v18
	v_fma_f32 v26, v52, v16, v21
	v_sub_f32_e32 v16, v25, v10
	global_store_dword v[12:13], v4, off offset:3456
	v_lshlrev_b32_e32 v4, 16, v105
	v_and_b32_e32 v5, 0xffff0000, v105
	v_fma_f32 v25, v53, v16, v10
	v_add_f32_e32 v16, 1.0, v17
	v_rcp_f32_e32 v16, v16
	v_pk_add_f32 v[8:9], v[8:9], v[4:5] neg_lo:[0,1] neg_hi:[0,1]
	v_add_f32_e32 v17, 1.0, v18
	v_pk_fma_f32 v[18:19], v[50:51], v[8:9], v[4:5]
	v_rcp_f32_e32 v17, v17
	v_pk_mul_f32 v[8:9], v[42:43], v[18:19]
	v_cvt_pk_bf16_f32 v20, v20, v22
	global_store_dword v[12:13], v20, off offset:3584
	v_pk_mul_f32 v[28:29], v[8:9], v[8:9]
	v_cvt_pk_bf16_f32 v20, v34, v35
	global_store_dword v[12:13], v20, off offset:3712
	v_add_f32_e32 v27, v28, v29
	v_add_f32_e32 v29, -1.0, v16
	v_fma_f32 v29, v40, v29, 1.0
	v_mul_f32_e32 v18, v18, v29
	v_add_f32_e32 v29, -1.0, v17
	v_fma_f32 v29, v41, v29, 1.0
	v_mul_f32_e32 v19, v19, v29
	v_mul_f32_e32 v30, v25, v19
	v_mul_f32_e32 v29, v26, v18
	v_mul_f32_e32 v30, v39, v30
	v_fmac_f32_e32 v30, v38, v29
	v_add_f32_dpp v27, v27, v27 quad_perm:[1,0,3,2] row_mask:0xf bank_mask:0xf bound_ctrl:1
	s_nop 0
	v_add_f32_dpp v29, v30, v30 quad_perm:[1,0,3,2] row_mask:0xf bank_mask:0xf bound_ctrl:1
	v_add_f32_dpp v27, v27, v27 quad_perm:[2,3,0,1] row_mask:0xf bank_mask:0xf bound_ctrl:1
	s_nop 0
	v_add_f32_dpp v29, v29, v29 quad_perm:[2,3,0,1] row_mask:0xf bank_mask:0xf bound_ctrl:1
	v_add_f32_dpp v27, v27, v27 row_half_mirror row_mask:0xf bank_mask:0xf bound_ctrl:1
	s_nop 0
	v_add_f32_dpp v29, v29, v29 row_half_mirror row_mask:0xf bank_mask:0xf bound_ctrl:1
	v_add_f32_dpp v27, v27, v27 row_mirror row_mask:0xf bank_mask:0xf bound_ctrl:1
	ds_bpermute_b32 v28, v96, v27
	v_add_f32_dpp v29, v29, v29 row_mirror row_mask:0xf bank_mask:0xf bound_ctrl:1
	ds_bpermute_b32 v30, v96, v29
	s_and_saveexec_b64 s[42:43], s[6:7]
	s_cbranch_execz .LBB0_496
	s_lshl_b64 s[58:59], s[58:59], 6
	v_lshl_add_u64 v[12:13], v[68:69], 0, s[58:59]
	s_waitcnt lgkmcnt(0)
	v_add_f32_e32 v20, v29, v30
	global_store_dword v[12:13], v20, off
; __device__ __forceinline__ float bflo(unsigned u) { return __uint_as_float(u << 16); }
; __global__ void __launch_bounds__(NWAVES * 64, 2) mk_fwd(Args args) {
;     ...
;                     for (int tok = 0; tok < 16; ++tok) {
;                         const int m = m0 + tok;
;                         const unsigned ur = pur[tok + 1], uk = puk[tok + 1], uv = puv[tok + 1];
;                         const float cr[2] = {bflo(ur), bfhi(ur)}, ck[2] = {bflo(uk), bfhi(uk)}, cv[2] = {bflo(uv), bfhi(uv)};
;                         float rr[2], kk[2], vv[2], dec[2], aa[2], kkn[2], km[2], bb[2];
;                         rr[0] = cr[0] + (pr[0] - cr[0]) * mu_r.x; rr[1] = cr[1] + (pr[1] - cr[1]) * mu_r.y;
;                         kk[0] = ck[0] + (pk[0] - ck[0]) * mu_k.x; kk[1] = ck[1] + (pk[1] - ck[1]) * mu_k.y;
;                         vv[0] = cv[0] + (pv[0] - cv[0]) * mu_v.x; vv[1] = cv[1] + (pv[1] - cv[1]) * mu_v.y;
;                         dec[0] = __expf(-0.6065306597126334f * sigmoidf_(w0v.x + lw[tok][0])); dec[1] = __expf(-0.6065306597126334f * sigmoidf_(w0v.y + lw[tok][1]));
;                         aa[0] = sigmoidf_(a0v.x + la[tok][0]); aa[1] = sigmoidf_(a0v.y + la[tok][1]);
;                         kkn[0] = kk[0] * kkw.x; kkn[1] = kk[1] * kkw.y;
;                         const float ssq = sum32(kkn[0] * kkn[0] + kkn[1] * kkn[1]);
;                         const float inv = rsqrtf(ssq + 1e-12f);
;                         kkn[0] *= inv; kkn[1] *= inv;
;                         km[0] = kk[0] * (1.f + (aa[0] - 1.f) * kaw.x); km[1] = kk[1] * (1.f + (aa[1] - 1.f) * kaw.y);
;                         bb[0] = kkn[0] * aa[0]; bb[1] = kkn[1] * aa[1];
;                         const float rkd = sum32(rr[0] * km[0] * rkw.x + rr[1] * km[1] * rkw.y);
;                         if (kp == 0) rkdot[(size_t)m * 16 + h] = rkd;
;                         char* rec = scanrec + (rec0 + tok) * REC;
;                         *(f32x2*)(rec + kp * 8) = (f32x2){dec[0], dec[1]};
;                         *(f32x2*)(rec + 256 + kp * 8) = (f32x2){kkn[0], kkn[1]};
;                         *(f32x2*)(rec + 512 + kp * 8) = (f32x2){bb[0], bb[1]};
;                         *(unsigned*)(rec + 768 + kp * 4) = cvtpk(rr[0], rr[1]);
;                         *(unsigned*)(rec + 896 + kp * 4) = cvtpk(km[0], km[1]);
;                         *(unsigned*)(rec + 1024 + kp * 4) = cvtpk(vv[0], vv[1]);
.LBB0_496:
	s_or_b64 exec, exec, s[42:43]
	s_nop 0
	v_lshlrev_b32_e32 v12, 16, v104
	s_nop 0
	v_and_b32_e32 v6, 0xffff0000, v104
	v_add_f32_e32 v20, v46, v108
	v_mul_f32_e32 v20, 0xbfb8aa3b, v20
	v_exp_f32_e32 v20, v20
	v_sub_f32_e32 v13, v24, v12
	s_waitcnt lgkmcnt(0)
	v_fma_f32 v30, v48, v13, v12
	v_sub_f32_e32 v13, v23, v6
	v_fma_f32 v31, v49, v13, v6
	v_add_f32_e32 v13, 1.0, v20
	v_rcp_f32_e32 v13, v13
	v_add_f32_e32 v20, v47, v107
	v_mul_f32_e32 v20, 0xbfb8aa3b, v20
	v_exp_f32_e32 v20, v20
	v_mul_f32_e32 v13, 0xbf1b4598, v13
	v_mul_f32_e32 v13, 0x3fb8aa3b, v13
	v_exp_f32_e32 v22, v13
	v_add_f32_e32 v13, 1.0, v20
	v_add_f32_e32 v20, v27, v28
	v_add_f32_e32 v20, 0x2b8cbccc, v20
	v_rcp_f32_e32 v13, v13
	v_mul_f32_e32 v23, 0x4b800000, v20
	v_cmp_gt_f32_e32 vcc, s33, v20
	s_movk_i32 s42, 0x4000
	v_mul_f32_e32 v13, 0xbf1b4598, v13
	v_cndmask_b32_e32 v20, v20, v23, vcc
	v_rsq_f32_e32 v20, v20
	v_mul_f32_e32 v13, 0x3fb8aa3b, v13
	v_exp_f32_e32 v23, v13
	s_nop 0
	v_mul_f32_e32 v13, 0x45800000, v20
	v_cndmask_b32_e32 v20, v20, v13, vcc
	v_pk_mul_f32 v[28:29], v[8:9], v[20:21] op_sel_hi:[1,0]
	v_add_co_u32_e32 v8, vcc, s42, v78
	v_pk_mul_f32 v[16:17], v[16:17], v[28:29]
	s_nop 0
	v_addc_co_u32_e32 v9, vcc, 0, v79, vcc
	v_add_co_u32_e32 v24, vcc, s42, v32
	s_nop 0
	global_store_dwordx2 v[14:15], v[22:23], off offset:3840
	global_store_dwordx2 v[8:9], v[28:29], off
	global_store_dwordx2 v[8:9], v[16:17], off offset:256
	v_cvt_pk_bf16_f32 v11, v26, v25
	v_addc_co_u32_e32 v25, vcc, 0, v33, vcc
	v_lshlrev_b32_e32 v13, 16, v99
	global_store_dword v[24:25], v11, off offset:512
	v_sub_f32_e32 v11, v21, v13
	v_fmac_f32_e32 v13, v52, v11
	v_add_f32_e32 v11, v44, v103
	v_add_f32_e32 v15, v45, v102
	v_mul_f32_e32 v11, 0xbfb8aa3b, v11
	v_mul_f32_e32 v15, 0xbfb8aa3b, v15
	v_exp_f32_e32 v11, v11
	v_exp_f32_e32 v15, v15
	v_lshlrev_b32_e32 v16, 16, v98
	v_and_b32_e32 v17, 0xffff0000, v98
	v_and_b32_e32 v14, 0xffff0000, v99
	v_pk_add_f32 v[4:5], v[4:5], v[16:17] neg_lo:[0,1] neg_hi:[0,1]
	v_sub_f32_e32 v10, v10, v14
	v_pk_fma_f32 v[22:23], v[50:51], v[4:5], v[16:17]
	v_fmac_f32_e32 v14, v53, v10
	v_add_f32_e32 v10, 1.0, v11
	v_add_f32_e32 v11, 1.0, v15
	v_pk_mul_f32 v[4:5], v[42:43], v[22:23]
	v_rcp_f32_e32 v11, v11
	v_pk_mul_f32 v[16:17], v[4:5], v[4:5]
	v_rcp_f32_e32 v10, v10
	v_add_f32_e32 v15, v16, v17
	v_add_f32_e32 v16, -1.0, v11
	v_fma_f32 v16, v41, v16, 1.0
	v_add_f32_dpp v15, v15, v15 quad_perm:[1,0,3,2] row_mask:0xf bank_mask:0xf bound_ctrl:1
	v_mul_f32_e32 v16, v23, v16
	v_cvt_pk_bf16_f32 v18, v18, v19
	global_store_dword v[24:25], v18, off offset:640
	v_add_f32_dpp v15, v15, v15 quad_perm:[2,3,0,1] row_mask:0xf bank_mask:0xf bound_ctrl:1
	v_cvt_pk_bf16_f32 v18, v30, v31
	global_store_dword v[24:25], v18, off offset:768
	s_nop 0
	v_add_f32_dpp v15, v15, v15 row_half_mirror row_mask:0xf bank_mask:0xf bound_ctrl:1
	s_nop 1
	v_add_f32_dpp v17, v15, v15 row_mirror row_mask:0xf bank_mask:0xf bound_ctrl:1
	v_add_f32_e32 v15, -1.0, v10
	v_fma_f32 v15, v40, v15, 1.0
	v_mul_f32_e32 v15, v22, v15
	v_mul_f32_e32 v22, v14, v16
	v_mul_f32_e32 v21, v13, v15
	v_mul_f32_e32 v22, v39, v22
	v_fmac_f32_e32 v22, v38, v21
	ds_bpermute_b32 v20, v96, v17
	s_nop 0
	v_add_f32_dpp v21, v22, v22 quad_perm:[1,0,3,2] row_mask:0xf bank_mask:0xf bound_ctrl:1
	s_nop 1
	v_add_f32_dpp v21, v21, v21 quad_perm:[2,3,0,1] row_mask:0xf bank_mask:0xf bound_ctrl:1
	s_nop 1
	v_add_f32_dpp v21, v21, v21 row_half_mirror row_mask:0xf bank_mask:0xf bound_ctrl:1
	s_nop 1
	v_add_f32_dpp v21, v21, v21 row_mirror row_mask:0xf bank_mask:0xf bound_ctrl:1
	ds_bpermute_b32 v22, v96, v21
	s_and_saveexec_b64 s[42:43], s[6:7]
	s_cbranch_execz .LBB0_424
	s_lshl_b64 s[56:57], s[56:57], 6
	v_lshl_add_u64 v[18:19], v[68:69], 0, s[56:57]
	s_waitcnt lgkmcnt(0)
	v_add_f32_e32 v21, v21, v22
	global_store_dword v[18:19], v21, off
	s_branch .LBB0_424
